# v7: K-loops: loader half at setprio 2 during load segments; redundant post-barrier lgkmcnt(0) removed
# speedup vs baseline: 1.0032x; 1.0032x over previous
.LBB0_271:
	s_add_u32 s26, s14, 0xfffc0080
	s_addc_u32 s27, s15, -1
	s_add_i32 s54, 0, 0x10000
	s_cmp_eq_u32 s53, 12
	s_cselect_b32 s29, s21, s27
	s_cselect_b32 s28, s49, s26
	v_add_u32_e32 v154, s54, v141
	s_cselect_b32 s27, s19, s52
	s_cselect_b32 s26, s50, s51
	s_add_i32 s56, 0, 0x14000
	ds_read_b128 v[146:149], v154
	ds_read_b128 v[150:153], v154 offset:1024
	ds_read_b128 v[162:165], v154 offset:2048
	ds_read_b128 v[166:169], v154 offset:3072
	v_add_u32_e32 v154, s56, v141
	ds_read_b128 v[170:173], v154
	ds_read_b128 v[186:189], v154 offset:1024
	ds_read_b128 v[190:193], v154 offset:2048
	ds_read_b128 v[194:197], v154 offset:3072
	v_lshl_add_u64 v[154:155], s[14:15], 0, v[136:137]
	s_add_i32 m0, s37, 0xc000
	ds_read_b128 v[198:201], v145
	ds_read_b128 v[202:205], v145 offset:1024
	ds_read_b128 v[206:209], v145 offset:2048
	ds_read_b128 v[210:213], v145 offset:3072
	ds_read_b128 v[214:217], v145 offset:4096
	ds_read_b128 v[218:221], v145 offset:5120
	ds_read_b128 v[222:225], v145 offset:6144
	ds_read_b128 v[226:229], v145 offset:7168
	global_load_lds_dwordx4 v[154:155], off
	v_lshl_add_u64 v[154:155], s[14:15], 0, v[138:139]
	s_add_i32 m0, s37, 0xe000
	s_nop 0
	global_load_lds_dwordx4 v[154:155], off
	s_setprio 0
	s_waitcnt vmcnt(8)
	s_waitcnt lgkmcnt(0)
	s_barrier
	s_setprio 1
	v_mfma_f32_16x16x32_bf16 v[126:129], v[146:149], v[198:201], v[126:129]
	v_mfma_f32_16x16x32_bf16 v[122:125], v[162:165], v[198:201], v[122:125]
	v_mfma_f32_16x16x32_bf16 v[110:113], v[146:149], v[206:209], v[110:113]
	v_mfma_f32_16x16x32_bf16 v[106:109], v[162:165], v[206:209], v[106:109]
	v_mfma_f32_16x16x32_bf16 v[92:95], v[146:149], v[214:217], v[92:95]
	v_mfma_f32_16x16x32_bf16 v[88:91], v[162:165], v[214:217], v[88:91]
	v_mfma_f32_16x16x32_bf16 v[76:79], v[146:149], v[222:225], v[76:79]
	v_mfma_f32_16x16x32_bf16 v[72:75], v[162:165], v[222:225], v[72:75]
	v_mfma_f32_16x16x32_bf16 v[126:129], v[150:153], v[202:205], v[126:129]
	v_mfma_f32_16x16x32_bf16 v[122:125], v[166:169], v[202:205], v[122:125]
	v_mfma_f32_16x16x32_bf16 v[110:113], v[150:153], v[210:213], v[110:113]
	v_mfma_f32_16x16x32_bf16 v[106:109], v[166:169], v[210:213], v[106:109]
	v_mfma_f32_16x16x32_bf16 v[92:95], v[150:153], v[218:221], v[92:95]
	v_mfma_f32_16x16x32_bf16 v[88:91], v[166:169], v[218:221], v[88:91]
	v_mfma_f32_16x16x32_bf16 v[76:79], v[150:153], v[226:229], v[76:79]
	v_mfma_f32_16x16x32_bf16 v[72:75], v[166:169], v[226:229], v[72:75]
	s_setprio 0
	s_setprio 1
	v_mfma_f32_16x16x32_bf16 v[118:121], v[170:173], v[198:201], v[118:121]
	v_mfma_f32_16x16x32_bf16 v[114:117], v[190:193], v[198:201], v[114:117]
	v_mfma_f32_16x16x32_bf16 v[102:105], v[170:173], v[206:209], v[102:105]
	v_mfma_f32_16x16x32_bf16 v[98:101], v[190:193], v[206:209], v[98:101]
	v_mfma_f32_16x16x32_bf16 v[84:87], v[170:173], v[214:217], v[84:87]
	v_mfma_f32_16x16x32_bf16 v[80:83], v[190:193], v[214:217], v[80:83]
	v_mfma_f32_16x16x32_bf16 v[68:71], v[170:173], v[222:225], v[68:71]
	v_mfma_f32_16x16x32_bf16 v[64:67], v[190:193], v[222:225], v[64:67]
	v_mfma_f32_16x16x32_bf16 v[118:121], v[186:189], v[202:205], v[118:121]
	v_mfma_f32_16x16x32_bf16 v[114:117], v[194:197], v[202:205], v[114:117]
	v_mfma_f32_16x16x32_bf16 v[102:105], v[186:189], v[210:213], v[102:105]
	v_mfma_f32_16x16x32_bf16 v[98:101], v[194:197], v[210:213], v[98:101]
	v_mfma_f32_16x16x32_bf16 v[84:87], v[186:189], v[218:221], v[84:87]
	v_mfma_f32_16x16x32_bf16 v[80:83], v[194:197], v[218:221], v[80:83]
	v_mfma_f32_16x16x32_bf16 v[68:71], v[186:189], v[226:229], v[68:71]
	v_mfma_f32_16x16x32_bf16 v[64:67], v[194:197], v[226:229], v[64:67]
	s_setprio 0
	s_barrier
	s_setprio 2
	s_add_i32 s54, s54, s36
	v_lshl_add_u64 v[154:155], s[26:27], 0, v[96:97]
	s_mov_b32 m0, s54
	ds_read_b128 v[198:201], v145 offset:16384
	ds_read_b128 v[202:205], v145 offset:17408
	ds_read_b128 v[206:209], v145 offset:18432
	ds_read_b128 v[210:213], v145 offset:19456
	ds_read_b128 v[214:217], v145 offset:20480
	ds_read_b128 v[218:221], v145 offset:21504
	ds_read_b128 v[222:225], v145 offset:22528
	ds_read_b128 v[226:229], v145 offset:23552
	global_load_lds_dwordx4 v[154:155], off
	s_add_i32 m0, s54, 0x2000
	s_add_u32 s54, s26, 0x40000
	v_lshl_add_u64 v[156:157], s[26:27], 0, v[130:131]
	s_addc_u32 s55, s27, 0
	s_add_i32 s56, s56, s36
	global_load_lds_dwordx4 v[156:157], off
	v_lshl_add_u64 v[158:159], s[54:55], 0, v[96:97]
	s_mov_b32 m0, s56
	v_lshl_add_u64 v[182:183], s[28:29], 0, v[132:133]
	global_load_lds_dwordx4 v[158:159], off
	v_lshl_add_u64 v[158:159], s[54:55], 0, v[130:131]
	s_add_i32 m0, s56, 0x2000
	s_nop 0
	global_load_lds_dwordx4 v[158:159], off
	v_lshl_add_u64 v[158:159], s[28:29], 0, v[134:135]
	s_mov_b32 m0, s37
	s_nop 0
	global_load_lds_dwordx4 v[158:159], off
	s_mov_b32 m0, s38
	s_nop 0
	global_load_lds_dwordx4 v[182:183], off
	s_setprio 0
	s_waitcnt vmcnt(8)
	s_waitcnt lgkmcnt(0)
	s_barrier
	s_setprio 1
	v_mfma_f32_16x16x32_bf16 v[60:63], v[146:149], v[198:201], v[60:63]
	v_mfma_f32_16x16x32_bf16 v[56:59], v[162:165], v[198:201], v[56:59]
	v_mfma_f32_16x16x32_bf16 v[44:47], v[146:149], v[206:209], v[44:47]
	v_mfma_f32_16x16x32_bf16 v[40:43], v[162:165], v[206:209], v[40:43]
	v_mfma_f32_16x16x32_bf16 v[28:31], v[146:149], v[214:217], v[28:31]
	v_mfma_f32_16x16x32_bf16 v[24:27], v[162:165], v[214:217], v[24:27]
	v_mfma_f32_16x16x32_bf16 v[12:15], v[146:149], v[222:225], v[12:15]
	v_mfma_f32_16x16x32_bf16 v[4:7], v[162:165], v[222:225], v[4:7]
	v_mfma_f32_16x16x32_bf16 v[60:63], v[150:153], v[202:205], v[60:63]
	v_mfma_f32_16x16x32_bf16 v[56:59], v[166:169], v[202:205], v[56:59]
	v_mfma_f32_16x16x32_bf16 v[44:47], v[150:153], v[210:213], v[44:47]
	v_mfma_f32_16x16x32_bf16 v[40:43], v[166:169], v[210:213], v[40:43]
	v_mfma_f32_16x16x32_bf16 v[28:31], v[150:153], v[218:221], v[28:31]
	v_mfma_f32_16x16x32_bf16 v[24:27], v[166:169], v[218:221], v[24:27]
	v_mfma_f32_16x16x32_bf16 v[12:15], v[150:153], v[226:229], v[12:15]
	v_mfma_f32_16x16x32_bf16 v[4:7], v[166:169], v[226:229], v[4:7]
	s_setprio 0
	s_setprio 1
	v_mfma_f32_16x16x32_bf16 v[52:55], v[170:173], v[198:201], v[52:55]
	v_mfma_f32_16x16x32_bf16 v[48:51], v[190:193], v[198:201], v[48:51]
	v_mfma_f32_16x16x32_bf16 v[36:39], v[170:173], v[206:209], v[36:39]
	v_mfma_f32_16x16x32_bf16 v[32:35], v[190:193], v[206:209], v[32:35]
	v_mfma_f32_16x16x32_bf16 v[20:23], v[170:173], v[214:217], v[20:23]
	v_mfma_f32_16x16x32_bf16 v[16:19], v[190:193], v[214:217], v[16:19]
	v_mfma_f32_16x16x32_bf16 v[8:11], v[170:173], v[222:225], v[8:11]
	v_mfma_f32_16x16x32_bf16 v[0:3], v[190:193], v[222:225], v[0:3]
	v_mfma_f32_16x16x32_bf16 v[52:55], v[186:189], v[202:205], v[52:55]
	v_mfma_f32_16x16x32_bf16 v[48:51], v[194:197], v[202:205], v[48:51]
	v_mfma_f32_16x16x32_bf16 v[36:39], v[186:189], v[210:213], v[36:39]
	v_mfma_f32_16x16x32_bf16 v[32:35], v[194:197], v[210:213], v[32:35]
	v_mfma_f32_16x16x32_bf16 v[20:23], v[186:189], v[218:221], v[20:23]
	v_mfma_f32_16x16x32_bf16 v[16:19], v[194:197], v[218:221], v[16:19]
	v_mfma_f32_16x16x32_bf16 v[8:11], v[186:189], v[226:229], v[8:11]
	v_mfma_f32_16x16x32_bf16 v[0:3], v[194:197], v[226:229], v[0:3]
	s_setprio 0
	s_barrier
	s_setprio 2
	s_add_i32 s54, 0, 0x18000
	s_add_i32 s55, 0, 0x1c000
	v_add_u32_e32 v166, s54, v141
	v_add_u32_e32 v184, s55, v141
	ds_read_b128 v[146:149], v166
	ds_read_b128 v[150:153], v166 offset:1024
	ds_read_b128 v[162:165], v166 offset:2048
	ds_read_b128 v[166:169], v166 offset:3072
	ds_read_b128 v[170:173], v184
	ds_read_b128 v[186:189], v184 offset:1024
	ds_read_b128 v[190:193], v184 offset:2048
	ds_read_b128 v[194:197], v184 offset:3072
	s_add_u32 s28, s28, 0x40000
	s_addc_u32 s29, s29, 0
	s_mov_b32 m0, s39
	v_lshl_add_u64 v[184:185], s[28:29], 0, v[134:135]
	ds_read_b128 v[198:201], v145 offset:32768
	ds_read_b128 v[202:205], v145 offset:33792
	ds_read_b128 v[206:209], v145 offset:34816
	ds_read_b128 v[210:213], v145 offset:35840
	ds_read_b128 v[214:217], v145 offset:36864
	ds_read_b128 v[218:221], v145 offset:37888
	ds_read_b128 v[222:225], v145 offset:38912
	ds_read_b128 v[226:229], v145 offset:39936
	global_load_lds_dwordx4 v[184:185], off
	v_lshl_add_u64 v[184:185], s[28:29], 0, v[132:133]
	s_mov_b32 m0, s40
	s_nop 0
	global_load_lds_dwordx4 v[184:185], off
	s_setprio 0
	s_waitcnt vmcnt(8)
	s_waitcnt lgkmcnt(0)
	s_barrier
	s_setprio 1
	v_mfma_f32_16x16x32_bf16 v[126:129], v[146:149], v[198:201], v[126:129]
	v_mfma_f32_16x16x32_bf16 v[122:125], v[162:165], v[198:201], v[122:125]
	v_mfma_f32_16x16x32_bf16 v[110:113], v[146:149], v[206:209], v[110:113]
	v_mfma_f32_16x16x32_bf16 v[106:109], v[162:165], v[206:209], v[106:109]
	v_mfma_f32_16x16x32_bf16 v[92:95], v[146:149], v[214:217], v[92:95]
	v_mfma_f32_16x16x32_bf16 v[88:91], v[162:165], v[214:217], v[88:91]
	v_mfma_f32_16x16x32_bf16 v[76:79], v[146:149], v[222:225], v[76:79]
	v_mfma_f32_16x16x32_bf16 v[72:75], v[162:165], v[222:225], v[72:75]
	v_mfma_f32_16x16x32_bf16 v[126:129], v[150:153], v[202:205], v[126:129]
	v_mfma_f32_16x16x32_bf16 v[122:125], v[166:169], v[202:205], v[122:125]
	v_mfma_f32_16x16x32_bf16 v[110:113], v[150:153], v[210:213], v[110:113]
	v_mfma_f32_16x16x32_bf16 v[106:109], v[166:169], v[210:213], v[106:109]
	v_mfma_f32_16x16x32_bf16 v[92:95], v[150:153], v[218:221], v[92:95]
	v_mfma_f32_16x16x32_bf16 v[88:91], v[166:169], v[218:221], v[88:91]
	v_mfma_f32_16x16x32_bf16 v[76:79], v[150:153], v[226:229], v[76:79]
	v_mfma_f32_16x16x32_bf16 v[72:75], v[166:169], v[226:229], v[72:75]
	s_setprio 0
	s_setprio 1
	v_mfma_f32_16x16x32_bf16 v[118:121], v[170:173], v[198:201], v[118:121]
	v_mfma_f32_16x16x32_bf16 v[114:117], v[190:193], v[198:201], v[114:117]
	v_mfma_f32_16x16x32_bf16 v[102:105], v[170:173], v[206:209], v[102:105]
	v_mfma_f32_16x16x32_bf16 v[98:101], v[190:193], v[206:209], v[98:101]
	v_mfma_f32_16x16x32_bf16 v[84:87], v[170:173], v[214:217], v[84:87]
	v_mfma_f32_16x16x32_bf16 v[80:83], v[190:193], v[214:217], v[80:83]
	v_mfma_f32_16x16x32_bf16 v[68:71], v[170:173], v[222:225], v[68:71]
	v_mfma_f32_16x16x32_bf16 v[64:67], v[190:193], v[222:225], v[64:67]
	v_mfma_f32_16x16x32_bf16 v[118:121], v[186:189], v[202:205], v[118:121]
	v_mfma_f32_16x16x32_bf16 v[114:117], v[194:197], v[202:205], v[114:117]
	v_mfma_f32_16x16x32_bf16 v[102:105], v[186:189], v[210:213], v[102:105]
	v_mfma_f32_16x16x32_bf16 v[98:101], v[194:197], v[210:213], v[98:101]
	v_mfma_f32_16x16x32_bf16 v[84:87], v[186:189], v[218:221], v[84:87]
	v_mfma_f32_16x16x32_bf16 v[80:83], v[194:197], v[218:221], v[80:83]
	v_mfma_f32_16x16x32_bf16 v[68:71], v[186:189], v[226:229], v[68:71]
	v_mfma_f32_16x16x32_bf16 v[64:67], v[194:197], v[226:229], v[64:67]
	s_setprio 0
	s_barrier
	s_setprio 2
	s_add_i32 s28, s54, s36
	v_lshl_add_u64 v[154:155], v[154:155], 0, s[16:17]
	s_mov_b32 m0, s28
	ds_read_b128 v[198:201], v145 offset:49152
	ds_read_b128 v[202:205], v145 offset:50176
	ds_read_b128 v[206:209], v145 offset:51200
	ds_read_b128 v[210:213], v145 offset:52224
	ds_read_b128 v[214:217], v145 offset:53248
	ds_read_b128 v[218:221], v145 offset:54272
	ds_read_b128 v[222:225], v145 offset:55296
	ds_read_b128 v[226:229], v145 offset:56320
	global_load_lds_dwordx4 v[154:155], off
	s_add_i32 m0, s28, 0x2000
	s_add_u32 s26, s26, 0x40080
	v_lshl_add_u64 v[154:155], v[156:157], 0, s[16:17]
	s_addc_u32 s27, s27, 0
	s_add_i32 s28, s55, s36
	global_load_lds_dwordx4 v[154:155], off
	v_lshl_add_u64 v[154:155], s[26:27], 0, v[96:97]
	s_mov_b32 m0, s28
	s_nop 0
	global_load_lds_dwordx4 v[154:155], off
	v_lshl_add_u64 v[154:155], s[26:27], 0, v[130:131]
	s_add_i32 m0, s28, 0x2000
	s_nop 0
	global_load_lds_dwordx4 v[154:155], off
	v_lshl_add_u64 v[154:155], v[158:159], 0, s[16:17]
	s_mov_b32 m0, s41
	s_nop 0
	global_load_lds_dwordx4 v[154:155], off
	v_lshl_add_u64 v[154:155], v[182:183], 0, s[16:17]
	s_mov_b32 m0, s42
	s_nop 0
	global_load_lds_dwordx4 v[154:155], off
	s_setprio 0
	s_waitcnt vmcnt(8)
	s_waitcnt lgkmcnt(0)
	s_barrier
	s_setprio 1
	v_mfma_f32_16x16x32_bf16 v[60:63], v[146:149], v[198:201], v[60:63]
	v_mfma_f32_16x16x32_bf16 v[56:59], v[162:165], v[198:201], v[56:59]
	v_mfma_f32_16x16x32_bf16 v[44:47], v[146:149], v[206:209], v[44:47]
	v_mfma_f32_16x16x32_bf16 v[40:43], v[162:165], v[206:209], v[40:43]
	v_mfma_f32_16x16x32_bf16 v[28:31], v[146:149], v[214:217], v[28:31]
	v_mfma_f32_16x16x32_bf16 v[24:27], v[162:165], v[214:217], v[24:27]
	v_mfma_f32_16x16x32_bf16 v[12:15], v[146:149], v[222:225], v[12:15]
	v_mfma_f32_16x16x32_bf16 v[4:7], v[162:165], v[222:225], v[4:7]
	v_mfma_f32_16x16x32_bf16 v[60:63], v[150:153], v[202:205], v[60:63]
	v_mfma_f32_16x16x32_bf16 v[56:59], v[166:169], v[202:205], v[56:59]
	v_mfma_f32_16x16x32_bf16 v[44:47], v[150:153], v[210:213], v[44:47]
	v_mfma_f32_16x16x32_bf16 v[40:43], v[166:169], v[210:213], v[40:43]
	v_mfma_f32_16x16x32_bf16 v[28:31], v[150:153], v[218:221], v[28:31]
	v_mfma_f32_16x16x32_bf16 v[24:27], v[166:169], v[218:221], v[24:27]
	v_mfma_f32_16x16x32_bf16 v[12:15], v[150:153], v[226:229], v[12:15]
	v_mfma_f32_16x16x32_bf16 v[4:7], v[166:169], v[226:229], v[4:7]
	s_setprio 0
	s_setprio 1
	v_mfma_f32_16x16x32_bf16 v[52:55], v[170:173], v[198:201], v[52:55]
	v_mfma_f32_16x16x32_bf16 v[48:51], v[190:193], v[198:201], v[48:51]
	v_mfma_f32_16x16x32_bf16 v[36:39], v[170:173], v[206:209], v[36:39]
	v_mfma_f32_16x16x32_bf16 v[32:35], v[190:193], v[206:209], v[32:35]
	v_mfma_f32_16x16x32_bf16 v[20:23], v[170:173], v[214:217], v[20:23]
	v_mfma_f32_16x16x32_bf16 v[16:19], v[190:193], v[214:217], v[16:19]
	v_mfma_f32_16x16x32_bf16 v[8:11], v[170:173], v[222:225], v[8:11]
	v_mfma_f32_16x16x32_bf16 v[0:3], v[190:193], v[222:225], v[0:3]
	v_mfma_f32_16x16x32_bf16 v[52:55], v[186:189], v[202:205], v[52:55]
	v_mfma_f32_16x16x32_bf16 v[48:51], v[194:197], v[202:205], v[48:51]
	v_mfma_f32_16x16x32_bf16 v[36:39], v[186:189], v[210:213], v[36:39]
	v_mfma_f32_16x16x32_bf16 v[32:35], v[194:197], v[210:213], v[32:35]
	v_mfma_f32_16x16x32_bf16 v[20:23], v[186:189], v[218:221], v[20:23]
	v_mfma_f32_16x16x32_bf16 v[16:19], v[194:197], v[218:221], v[16:19]
	v_mfma_f32_16x16x32_bf16 v[8:11], v[186:189], v[226:229], v[8:11]
	v_mfma_f32_16x16x32_bf16 v[0:3], v[194:197], v[226:229], v[0:3]
	s_setprio 0
	s_barrier
	s_setprio 2
	s_add_i32 s53, s53, 2
	s_add_u32 s14, s14, 0x100
	s_addc_u32 s15, s15, 0
	s_add_u32 s51, s51, 0x100
	s_addc_u32 s52, s52, 0
	s_cmp_gt_u32 s53, 13
	s_cbranch_scc0 .LBB0_271
	s_and_b64 vcc, exec, s[12:13]
	s_cbranch_vccz .LBB0_274
	s_barrier

.LBB0_361:
	s_add_u32 s34, s30, 0xfffc0080
	s_addc_u32 s35, s31, -1
	s_add_i32 s62, 0, 0x10000
	s_cmp_eq_u32 s61, 12
	s_cselect_b32 s37, s25, s35
	s_cselect_b32 s36, s57, s34
	v_add_u32_e32 v96, s62, v151
	s_cselect_b32 s35, s15, s60
	s_cselect_b32 s34, s58, s59
	s_add_i32 s64, 0, 0x14000
	ds_read_b128 v[164:167], v96
	ds_read_b128 v[168:171], v96 offset:1024
	ds_read_b128 v[186:189], v96 offset:2048
	ds_read_b128 v[190:193], v96 offset:3072
	v_add_u32_e32 v96, s64, v151
	ds_read_b128 v[194:197], v96
	ds_read_b128 v[198:201], v96 offset:1024
	ds_read_b128 v[202:205], v96 offset:2048
	ds_read_b128 v[206:209], v96 offset:3072
	v_lshl_add_u64 v[154:155], s[30:31], 0, v[146:147]
	s_add_i32 m0, s43, 0xc000
	ds_read_b128 v[210:213], v162
	ds_read_b128 v[214:217], v162 offset:1024
	ds_read_b128 v[218:221], v162 offset:2048
	ds_read_b128 v[222:225], v162 offset:3072
	ds_read_b128 v[226:229], v162 offset:4096
	ds_read_b128 v[230:233], v162 offset:5120
	ds_read_b128 v[242:245], v162 offset:6144
	ds_read_b128 v[246:249], v162 offset:7168
	global_load_lds_dwordx4 v[154:155], off
	v_lshl_add_u64 v[154:155], s[30:31], 0, v[148:149]
	s_add_i32 m0, s43, 0xe000
	s_nop 0
	global_load_lds_dwordx4 v[154:155], off
	s_setprio 0
	s_waitcnt vmcnt(8)
	s_waitcnt lgkmcnt(0)
	s_barrier
	s_setprio 1
	v_mfma_f32_16x16x32_bf16 v[126:129], v[164:167], v[210:213], v[126:129]
	v_mfma_f32_16x16x32_bf16 v[122:125], v[186:189], v[210:213], v[122:125]
	v_mfma_f32_16x16x32_bf16 v[118:121], v[164:167], v[218:221], v[118:121]
	v_mfma_f32_16x16x32_bf16 v[114:117], v[186:189], v[218:221], v[114:117]
	v_mfma_f32_16x16x32_bf16 v[110:113], v[164:167], v[226:229], v[110:113]
	v_mfma_f32_16x16x32_bf16 v[106:109], v[186:189], v[226:229], v[106:109]
	v_mfma_f32_16x16x32_bf16 v[102:105], v[164:167], v[242:245], v[102:105]
	v_mfma_f32_16x16x32_bf16 v[98:101], v[186:189], v[242:245], v[98:101]
	v_mfma_f32_16x16x32_bf16 v[126:129], v[168:171], v[214:217], v[126:129]
	v_mfma_f32_16x16x32_bf16 v[122:125], v[190:193], v[214:217], v[122:125]
	v_mfma_f32_16x16x32_bf16 v[118:121], v[168:171], v[222:225], v[118:121]
	v_mfma_f32_16x16x32_bf16 v[114:117], v[190:193], v[222:225], v[114:117]
	v_mfma_f32_16x16x32_bf16 v[110:113], v[168:171], v[230:233], v[110:113]
	v_mfma_f32_16x16x32_bf16 v[106:109], v[190:193], v[230:233], v[106:109]
	v_mfma_f32_16x16x32_bf16 v[102:105], v[168:171], v[246:249], v[102:105]
	v_mfma_f32_16x16x32_bf16 v[98:101], v[190:193], v[246:249], v[98:101]
	s_setprio 0
	s_setprio 1
	v_mfma_f32_16x16x32_bf16 v[76:79], v[194:197], v[210:213], v[76:79]
	v_mfma_f32_16x16x32_bf16 v[64:67], v[202:205], v[210:213], v[64:67]
	v_mfma_f32_16x16x32_bf16 v[60:63], v[194:197], v[218:221], v[60:63]
	v_mfma_f32_16x16x32_bf16 v[52:55], v[202:205], v[218:221], v[52:55]
	v_mfma_f32_16x16x32_bf16 v[44:47], v[194:197], v[226:229], v[44:47]
	v_mfma_f32_16x16x32_bf16 v[40:43], v[202:205], v[226:229], v[40:43]
	v_mfma_f32_16x16x32_bf16 v[36:39], v[194:197], v[242:245], v[36:39]
	v_mfma_f32_16x16x32_bf16 v[32:35], v[202:205], v[242:245], v[32:35]
	v_mfma_f32_16x16x32_bf16 v[76:79], v[198:201], v[214:217], v[76:79]
	v_mfma_f32_16x16x32_bf16 v[64:67], v[206:209], v[214:217], v[64:67]
	v_mfma_f32_16x16x32_bf16 v[60:63], v[198:201], v[222:225], v[60:63]
	v_mfma_f32_16x16x32_bf16 v[52:55], v[206:209], v[222:225], v[52:55]
	v_mfma_f32_16x16x32_bf16 v[44:47], v[198:201], v[230:233], v[44:47]
	v_mfma_f32_16x16x32_bf16 v[40:43], v[206:209], v[230:233], v[40:43]
	v_mfma_f32_16x16x32_bf16 v[36:39], v[198:201], v[246:249], v[36:39]
	v_mfma_f32_16x16x32_bf16 v[32:35], v[206:209], v[246:249], v[32:35]
	s_setprio 0
	s_barrier
	s_setprio 2
	s_add_i32 s62, s62, s40
	v_lshl_add_u64 v[154:155], s[34:35], 0, v[134:135]
	s_mov_b32 m0, s62
	ds_read_b128 v[210:213], v162 offset:16384
	ds_read_b128 v[214:217], v162 offset:17408
	ds_read_b128 v[218:221], v162 offset:18432
	ds_read_b128 v[222:225], v162 offset:19456
	ds_read_b128 v[226:229], v162 offset:20480
	ds_read_b128 v[230:233], v162 offset:21504
	ds_read_b128 v[242:245], v162 offset:22528
	ds_read_b128 v[246:249], v162 offset:23552
	global_load_lds_dwordx4 v[154:155], off
	s_add_i32 m0, s62, 0x2000
	s_add_u32 s62, s34, 0x40000
	v_lshl_add_u64 v[156:157], s[34:35], 0, v[130:131]
	s_addc_u32 s63, s35, 0
	s_add_i32 s64, s64, s40
	global_load_lds_dwordx4 v[156:157], off
	v_lshl_add_u64 v[158:159], s[62:63], 0, v[134:135]
	s_mov_b32 m0, s64
	v_lshl_add_u64 v[172:173], s[36:37], 0, v[132:133]
	global_load_lds_dwordx4 v[158:159], off
	v_lshl_add_u64 v[158:159], s[62:63], 0, v[130:131]
	s_add_i32 m0, s64, 0x2000
	s_nop 0
	global_load_lds_dwordx4 v[158:159], off
	v_lshl_add_u64 v[158:159], s[36:37], 0, v[136:137]
	s_mov_b32 m0, s43
	s_nop 0
	global_load_lds_dwordx4 v[158:159], off
	s_mov_b32 m0, s44
	s_nop 0
	global_load_lds_dwordx4 v[172:173], off
	s_setprio 0
	s_waitcnt vmcnt(8)
	s_waitcnt lgkmcnt(0)
	s_barrier
	s_setprio 1
	v_mfma_f32_16x16x32_bf16 v[92:95], v[164:167], v[210:213], v[92:95]
	v_mfma_f32_16x16x32_bf16 v[88:91], v[186:189], v[210:213], v[88:91]
	v_mfma_f32_16x16x32_bf16 v[84:87], v[164:167], v[218:221], v[84:87]
	v_mfma_f32_16x16x32_bf16 v[80:83], v[186:189], v[218:221], v[80:83]
	v_mfma_f32_16x16x32_bf16 v[72:75], v[164:167], v[226:229], v[72:75]
	v_mfma_f32_16x16x32_bf16 v[68:71], v[186:189], v[226:229], v[68:71]
	v_mfma_f32_16x16x32_bf16 v[56:59], v[164:167], v[242:245], v[56:59]
	v_mfma_f32_16x16x32_bf16 v[48:51], v[186:189], v[242:245], v[48:51]
	v_mfma_f32_16x16x32_bf16 v[92:95], v[168:171], v[214:217], v[92:95]
	v_mfma_f32_16x16x32_bf16 v[88:91], v[190:193], v[214:217], v[88:91]
	v_mfma_f32_16x16x32_bf16 v[84:87], v[168:171], v[222:225], v[84:87]
	v_mfma_f32_16x16x32_bf16 v[80:83], v[190:193], v[222:225], v[80:83]
	v_mfma_f32_16x16x32_bf16 v[72:75], v[168:171], v[230:233], v[72:75]
	v_mfma_f32_16x16x32_bf16 v[68:71], v[190:193], v[230:233], v[68:71]
	v_mfma_f32_16x16x32_bf16 v[56:59], v[168:171], v[246:249], v[56:59]
	v_mfma_f32_16x16x32_bf16 v[48:51], v[190:193], v[246:249], v[48:51]
	s_setprio 0
	s_setprio 1
	v_mfma_f32_16x16x32_bf16 v[28:31], v[194:197], v[210:213], v[28:31]
	v_mfma_f32_16x16x32_bf16 v[24:27], v[202:205], v[210:213], v[24:27]
	v_mfma_f32_16x16x32_bf16 v[20:23], v[194:197], v[218:221], v[20:23]
	v_mfma_f32_16x16x32_bf16 v[16:19], v[202:205], v[218:221], v[16:19]
	v_mfma_f32_16x16x32_bf16 v[12:15], v[194:197], v[226:229], v[12:15]
	v_mfma_f32_16x16x32_bf16 v[8:11], v[202:205], v[226:229], v[8:11]
	v_mfma_f32_16x16x32_bf16 v[4:7], v[194:197], v[242:245], v[4:7]
	v_mfma_f32_16x16x32_bf16 v[0:3], v[202:205], v[242:245], v[0:3]
	v_mfma_f32_16x16x32_bf16 v[28:31], v[198:201], v[214:217], v[28:31]
	v_mfma_f32_16x16x32_bf16 v[24:27], v[206:209], v[214:217], v[24:27]
	v_mfma_f32_16x16x32_bf16 v[20:23], v[198:201], v[222:225], v[20:23]
	v_mfma_f32_16x16x32_bf16 v[16:19], v[206:209], v[222:225], v[16:19]
	v_mfma_f32_16x16x32_bf16 v[12:15], v[198:201], v[230:233], v[12:15]
	v_mfma_f32_16x16x32_bf16 v[8:11], v[206:209], v[230:233], v[8:11]
	v_mfma_f32_16x16x32_bf16 v[4:7], v[198:201], v[246:249], v[4:7]
	v_mfma_f32_16x16x32_bf16 v[0:3], v[206:209], v[246:249], v[0:3]
	s_setprio 0
	s_barrier
	s_setprio 2
	s_add_i32 s62, 0, 0x18000
	v_add_u32_e32 v96, s62, v151
	s_add_i32 s63, 0, 0x1c000
	ds_read_b128 v[164:167], v96
	ds_read_b128 v[168:171], v96 offset:1024
	ds_read_b128 v[186:189], v96 offset:2048
	ds_read_b128 v[190:193], v96 offset:3072
	v_add_u32_e32 v96, s63, v151
	ds_read_b128 v[194:197], v96
	ds_read_b128 v[198:201], v96 offset:1024
	ds_read_b128 v[202:205], v96 offset:2048
	ds_read_b128 v[206:209], v96 offset:3072
	s_add_u32 s36, s36, 0x40000
	s_addc_u32 s37, s37, 0
	s_mov_b32 m0, s45
	v_lshl_add_u64 v[182:183], s[36:37], 0, v[136:137]
	ds_read_b128 v[210:213], v162 offset:32768
	ds_read_b128 v[214:217], v162 offset:33792
	ds_read_b128 v[218:221], v162 offset:34816
	ds_read_b128 v[222:225], v162 offset:35840
	ds_read_b128 v[226:229], v162 offset:36864
	ds_read_b128 v[230:233], v162 offset:37888
	ds_read_b128 v[242:245], v162 offset:38912
	ds_read_b128 v[246:249], v162 offset:39936
	global_load_lds_dwordx4 v[182:183], off
	v_lshl_add_u64 v[182:183], s[36:37], 0, v[132:133]
	s_mov_b32 m0, s46
	s_nop 0
	global_load_lds_dwordx4 v[182:183], off
	s_setprio 0
	s_waitcnt vmcnt(8)
	s_waitcnt lgkmcnt(0)
	s_barrier
	s_setprio 1
	v_mfma_f32_16x16x32_bf16 v[126:129], v[164:167], v[210:213], v[126:129]
	v_mfma_f32_16x16x32_bf16 v[122:125], v[186:189], v[210:213], v[122:125]
	v_mfma_f32_16x16x32_bf16 v[118:121], v[164:167], v[218:221], v[118:121]
	v_mfma_f32_16x16x32_bf16 v[114:117], v[186:189], v[218:221], v[114:117]
	v_mfma_f32_16x16x32_bf16 v[110:113], v[164:167], v[226:229], v[110:113]
	v_mfma_f32_16x16x32_bf16 v[106:109], v[186:189], v[226:229], v[106:109]
	v_mfma_f32_16x16x32_bf16 v[102:105], v[164:167], v[242:245], v[102:105]
	v_mfma_f32_16x16x32_bf16 v[98:101], v[186:189], v[242:245], v[98:101]
	v_mfma_f32_16x16x32_bf16 v[126:129], v[168:171], v[214:217], v[126:129]
	v_mfma_f32_16x16x32_bf16 v[122:125], v[190:193], v[214:217], v[122:125]
	v_mfma_f32_16x16x32_bf16 v[118:121], v[168:171], v[222:225], v[118:121]
	v_mfma_f32_16x16x32_bf16 v[114:117], v[190:193], v[222:225], v[114:117]
	v_mfma_f32_16x16x32_bf16 v[110:113], v[168:171], v[230:233], v[110:113]
	v_mfma_f32_16x16x32_bf16 v[106:109], v[190:193], v[230:233], v[106:109]
	v_mfma_f32_16x16x32_bf16 v[102:105], v[168:171], v[246:249], v[102:105]
	v_mfma_f32_16x16x32_bf16 v[98:101], v[190:193], v[246:249], v[98:101]
	s_setprio 0
	s_setprio 1
	v_mfma_f32_16x16x32_bf16 v[76:79], v[194:197], v[210:213], v[76:79]
	v_mfma_f32_16x16x32_bf16 v[64:67], v[202:205], v[210:213], v[64:67]
	v_mfma_f32_16x16x32_bf16 v[60:63], v[194:197], v[218:221], v[60:63]
	v_mfma_f32_16x16x32_bf16 v[52:55], v[202:205], v[218:221], v[52:55]
	v_mfma_f32_16x16x32_bf16 v[44:47], v[194:197], v[226:229], v[44:47]
	v_mfma_f32_16x16x32_bf16 v[40:43], v[202:205], v[226:229], v[40:43]
	v_mfma_f32_16x16x32_bf16 v[36:39], v[194:197], v[242:245], v[36:39]
	v_mfma_f32_16x16x32_bf16 v[32:35], v[202:205], v[242:245], v[32:35]
	v_mfma_f32_16x16x32_bf16 v[76:79], v[198:201], v[214:217], v[76:79]
	v_mfma_f32_16x16x32_bf16 v[64:67], v[206:209], v[214:217], v[64:67]
	v_mfma_f32_16x16x32_bf16 v[60:63], v[198:201], v[222:225], v[60:63]
	v_mfma_f32_16x16x32_bf16 v[52:55], v[206:209], v[222:225], v[52:55]
	v_mfma_f32_16x16x32_bf16 v[44:47], v[198:201], v[230:233], v[44:47]
	v_mfma_f32_16x16x32_bf16 v[40:43], v[206:209], v[230:233], v[40:43]
	v_mfma_f32_16x16x32_bf16 v[36:39], v[198:201], v[246:249], v[36:39]
	v_mfma_f32_16x16x32_bf16 v[32:35], v[206:209], v[246:249], v[32:35]
	s_setprio 0
	s_barrier
	s_setprio 2
	s_add_i32 s36, s62, s40
	v_lshl_add_u64 v[154:155], v[154:155], 0, s[16:17]
	s_mov_b32 m0, s36
	ds_read_b128 v[210:213], v162 offset:49152
	ds_read_b128 v[214:217], v162 offset:50176
	ds_read_b128 v[218:221], v162 offset:51200
	ds_read_b128 v[222:225], v162 offset:52224
	ds_read_b128 v[226:229], v162 offset:53248
	ds_read_b128 v[230:233], v162 offset:54272
	ds_read_b128 v[242:245], v162 offset:55296
	ds_read_b128 v[246:249], v162 offset:56320
	global_load_lds_dwordx4 v[154:155], off
	s_add_i32 m0, s36, 0x2000
	s_add_u32 s34, s34, 0x40080
	v_lshl_add_u64 v[154:155], v[156:157], 0, s[16:17]
	s_addc_u32 s35, s35, 0
	s_add_i32 s36, s63, s40
	global_load_lds_dwordx4 v[154:155], off
	v_lshl_add_u64 v[154:155], s[34:35], 0, v[134:135]
	s_mov_b32 m0, s36
	s_nop 0
	global_load_lds_dwordx4 v[154:155], off
	v_lshl_add_u64 v[154:155], s[34:35], 0, v[130:131]
	s_add_i32 m0, s36, 0x2000
	s_nop 0
	global_load_lds_dwordx4 v[154:155], off
	v_lshl_add_u64 v[154:155], v[158:159], 0, s[16:17]
	s_mov_b32 m0, s50
	s_nop 0
	global_load_lds_dwordx4 v[154:155], off
	v_lshl_add_u64 v[154:155], v[172:173], 0, s[16:17]
	s_mov_b32 m0, s51
	s_nop 0
	global_load_lds_dwordx4 v[154:155], off
	s_setprio 0
	s_waitcnt vmcnt(8)
	s_waitcnt lgkmcnt(0)
	s_barrier
	s_setprio 1
	v_mfma_f32_16x16x32_bf16 v[92:95], v[164:167], v[210:213], v[92:95]
	v_mfma_f32_16x16x32_bf16 v[88:91], v[186:189], v[210:213], v[88:91]
	v_mfma_f32_16x16x32_bf16 v[84:87], v[164:167], v[218:221], v[84:87]
	v_mfma_f32_16x16x32_bf16 v[80:83], v[186:189], v[218:221], v[80:83]
	v_mfma_f32_16x16x32_bf16 v[72:75], v[164:167], v[226:229], v[72:75]
	v_mfma_f32_16x16x32_bf16 v[68:71], v[186:189], v[226:229], v[68:71]
	v_mfma_f32_16x16x32_bf16 v[56:59], v[164:167], v[242:245], v[56:59]
	v_mfma_f32_16x16x32_bf16 v[48:51], v[186:189], v[242:245], v[48:51]
	v_mfma_f32_16x16x32_bf16 v[92:95], v[168:171], v[214:217], v[92:95]
	v_mfma_f32_16x16x32_bf16 v[88:91], v[190:193], v[214:217], v[88:91]
	v_mfma_f32_16x16x32_bf16 v[84:87], v[168:171], v[222:225], v[84:87]
	v_mfma_f32_16x16x32_bf16 v[80:83], v[190:193], v[222:225], v[80:83]
	v_mfma_f32_16x16x32_bf16 v[72:75], v[168:171], v[230:233], v[72:75]
	v_mfma_f32_16x16x32_bf16 v[68:71], v[190:193], v[230:233], v[68:71]
	v_mfma_f32_16x16x32_bf16 v[56:59], v[168:171], v[246:249], v[56:59]
	v_mfma_f32_16x16x32_bf16 v[48:51], v[190:193], v[246:249], v[48:51]
	s_setprio 0
	s_setprio 1
	v_mfma_f32_16x16x32_bf16 v[28:31], v[194:197], v[210:213], v[28:31]
	v_mfma_f32_16x16x32_bf16 v[24:27], v[202:205], v[210:213], v[24:27]
	v_mfma_f32_16x16x32_bf16 v[20:23], v[194:197], v[218:221], v[20:23]
	v_mfma_f32_16x16x32_bf16 v[16:19], v[202:205], v[218:221], v[16:19]
	v_mfma_f32_16x16x32_bf16 v[12:15], v[194:197], v[226:229], v[12:15]
	v_mfma_f32_16x16x32_bf16 v[8:11], v[202:205], v[226:229], v[8:11]
	v_mfma_f32_16x16x32_bf16 v[4:7], v[194:197], v[242:245], v[4:7]
	v_mfma_f32_16x16x32_bf16 v[0:3], v[202:205], v[242:245], v[0:3]
	v_mfma_f32_16x16x32_bf16 v[28:31], v[198:201], v[214:217], v[28:31]
	v_mfma_f32_16x16x32_bf16 v[24:27], v[206:209], v[214:217], v[24:27]
	v_mfma_f32_16x16x32_bf16 v[20:23], v[198:201], v[222:225], v[20:23]
	v_mfma_f32_16x16x32_bf16 v[16:19], v[206:209], v[222:225], v[16:19]
	v_mfma_f32_16x16x32_bf16 v[12:15], v[198:201], v[230:233], v[12:15]
	v_mfma_f32_16x16x32_bf16 v[8:11], v[206:209], v[230:233], v[8:11]
	v_mfma_f32_16x16x32_bf16 v[4:7], v[198:201], v[246:249], v[4:7]
	v_mfma_f32_16x16x32_bf16 v[0:3], v[206:209], v[246:249], v[0:3]
	s_setprio 0
	s_barrier
	s_setprio 2
	s_add_i32 s61, s61, 2
	s_add_u32 s30, s30, 0x100
	s_addc_u32 s31, s31, 0
	s_add_u32 s59, s59, 0x100
	s_addc_u32 s60, s60, 0
	s_cmp_gt_u32 s61, 13
	s_cbranch_scc0 .LBB0_361
	s_and_b64 vcc, exec, s[20:21]
	s_cbranch_vccz .LBB0_364
	s_barrier

.LBB0_393:
	s_add_u32 s26, s14, 0xfffc0080
	s_addc_u32 s27, s15, -1
	s_add_i32 s57, 0, 0x10000
	s_cmp_eq_u32 s56, 12
	s_cselect_b32 s29, s19, s27
	s_cselect_b32 s28, s52, s26
	v_add_u32_e32 v151, s57, v141
	s_cselect_b32 s27, s5, s55
	s_cselect_b32 s26, s53, s54
	s_add_i32 s60, 0, 0x14000
	ds_read_b128 v[162:165], v151
	ds_read_b128 v[166:169], v151 offset:1024
	ds_read_b128 v[170:173], v151 offset:2048
	ds_read_b128 v[186:189], v151 offset:3072
	v_add_u32_e32 v151, s60, v141
	ds_read_b128 v[190:193], v151
	ds_read_b128 v[194:197], v151 offset:1024
	ds_read_b128 v[198:201], v151 offset:2048
	ds_read_b128 v[202:205], v151 offset:3072
	v_lshl_add_u64 v[152:153], s[14:15], 0, v[146:147]
	s_add_i32 m0, s39, 0xc000
	ds_read_b128 v[206:209], v150
	ds_read_b128 v[210:213], v150 offset:1024
	ds_read_b128 v[214:217], v150 offset:2048
	ds_read_b128 v[218:221], v150 offset:3072
	ds_read_b128 v[222:225], v150 offset:4096
	ds_read_b128 v[226:229], v150 offset:5120
	ds_read_b128 v[230:233], v150 offset:6144
	ds_read_b128 v[242:245], v150 offset:7168
	global_load_lds_dwordx4 v[152:153], off
	v_lshl_add_u64 v[152:153], s[14:15], 0, v[148:149]
	s_add_i32 m0, s39, 0xe000
	s_nop 0
	global_load_lds_dwordx4 v[152:153], off
	s_setprio 0
	s_waitcnt vmcnt(8)
	s_waitcnt lgkmcnt(0)
	s_barrier
	s_setprio 1
	v_mfma_f32_16x16x32_bf16 v[126:129], v[162:165], v[206:209], v[126:129]
	v_mfma_f32_16x16x32_bf16 v[122:125], v[170:173], v[206:209], v[122:125]
	v_mfma_f32_16x16x32_bf16 v[118:121], v[162:165], v[214:217], v[118:121]
	v_mfma_f32_16x16x32_bf16 v[114:117], v[170:173], v[214:217], v[114:117]
	v_mfma_f32_16x16x32_bf16 v[110:113], v[162:165], v[222:225], v[110:113]
	v_mfma_f32_16x16x32_bf16 v[106:109], v[170:173], v[222:225], v[106:109]
	v_mfma_f32_16x16x32_bf16 v[102:105], v[162:165], v[230:233], v[102:105]
	v_mfma_f32_16x16x32_bf16 v[98:101], v[170:173], v[230:233], v[98:101]
	v_mfma_f32_16x16x32_bf16 v[126:129], v[166:169], v[210:213], v[126:129]
	v_mfma_f32_16x16x32_bf16 v[122:125], v[186:189], v[210:213], v[122:125]
	v_mfma_f32_16x16x32_bf16 v[118:121], v[166:169], v[218:221], v[118:121]
	v_mfma_f32_16x16x32_bf16 v[114:117], v[186:189], v[218:221], v[114:117]
	v_mfma_f32_16x16x32_bf16 v[110:113], v[166:169], v[226:229], v[110:113]
	v_mfma_f32_16x16x32_bf16 v[106:109], v[186:189], v[226:229], v[106:109]
	v_mfma_f32_16x16x32_bf16 v[102:105], v[166:169], v[242:245], v[102:105]
	v_mfma_f32_16x16x32_bf16 v[98:101], v[186:189], v[242:245], v[98:101]
	s_setprio 0
	s_setprio 1
	v_mfma_f32_16x16x32_bf16 v[68:71], v[190:193], v[206:209], v[68:71]
	v_mfma_f32_16x16x32_bf16 v[64:67], v[198:201], v[206:209], v[64:67]
	v_mfma_f32_16x16x32_bf16 v[52:55], v[190:193], v[214:217], v[52:55]
	v_mfma_f32_16x16x32_bf16 v[48:51], v[198:201], v[214:217], v[48:51]
	v_mfma_f32_16x16x32_bf16 v[44:47], v[190:193], v[222:225], v[44:47]
	v_mfma_f32_16x16x32_bf16 v[40:43], v[198:201], v[222:225], v[40:43]
	v_mfma_f32_16x16x32_bf16 v[36:39], v[190:193], v[230:233], v[36:39]
	v_mfma_f32_16x16x32_bf16 v[32:35], v[198:201], v[230:233], v[32:35]
	v_mfma_f32_16x16x32_bf16 v[68:71], v[194:197], v[210:213], v[68:71]
	v_mfma_f32_16x16x32_bf16 v[64:67], v[202:205], v[210:213], v[64:67]
	v_mfma_f32_16x16x32_bf16 v[52:55], v[194:197], v[218:221], v[52:55]
	v_mfma_f32_16x16x32_bf16 v[48:51], v[202:205], v[218:221], v[48:51]
	v_mfma_f32_16x16x32_bf16 v[44:47], v[194:197], v[226:229], v[44:47]
	v_mfma_f32_16x16x32_bf16 v[40:43], v[202:205], v[226:229], v[40:43]
	v_mfma_f32_16x16x32_bf16 v[36:39], v[194:197], v[242:245], v[36:39]
	v_mfma_f32_16x16x32_bf16 v[32:35], v[202:205], v[242:245], v[32:35]
	s_setprio 0
	s_barrier
	s_setprio 2
	s_add_i32 s57, s57, s36
	v_lshl_add_u64 v[152:153], s[26:27], 0, v[96:97]
	s_mov_b32 m0, s57
	ds_read_b128 v[206:209], v150 offset:16384
	ds_read_b128 v[210:213], v150 offset:17408
	ds_read_b128 v[214:217], v150 offset:18432
	ds_read_b128 v[218:221], v150 offset:19456
	ds_read_b128 v[222:225], v150 offset:20480
	ds_read_b128 v[226:229], v150 offset:21504
	ds_read_b128 v[230:233], v150 offset:22528
	ds_read_b128 v[242:245], v150 offset:23552
	global_load_lds_dwordx4 v[152:153], off
	s_add_i32 m0, s57, 0x2000
	s_add_u32 s58, s26, 0x40000
	v_lshl_add_u64 v[154:155], s[26:27], 0, v[130:131]
	s_addc_u32 s59, s27, 0
	s_add_i32 s57, s60, s36
	global_load_lds_dwordx4 v[154:155], off
	v_lshl_add_u64 v[156:157], s[58:59], 0, v[96:97]
	s_mov_b32 m0, s57
	v_lshl_add_u64 v[158:159], s[28:29], 0, v[132:133]
	global_load_lds_dwordx4 v[156:157], off
	v_lshl_add_u64 v[156:157], s[58:59], 0, v[130:131]
	s_add_i32 m0, s57, 0x2000
	s_nop 0
	global_load_lds_dwordx4 v[156:157], off
	v_lshl_add_u64 v[156:157], s[28:29], 0, v[134:135]
	s_mov_b32 m0, s39
	s_nop 0
	global_load_lds_dwordx4 v[156:157], off
	s_mov_b32 m0, s40
	s_nop 0
	global_load_lds_dwordx4 v[158:159], off
	s_setprio 0
	s_waitcnt vmcnt(8)
	s_waitcnt lgkmcnt(0)
	s_barrier
	s_setprio 1
	v_mfma_f32_16x16x32_bf16 v[92:95], v[162:165], v[206:209], v[92:95]
	v_mfma_f32_16x16x32_bf16 v[88:91], v[170:173], v[206:209], v[88:91]
	v_mfma_f32_16x16x32_bf16 v[84:87], v[162:165], v[214:217], v[84:87]
	v_mfma_f32_16x16x32_bf16 v[80:83], v[170:173], v[214:217], v[80:83]
	v_mfma_f32_16x16x32_bf16 v[76:79], v[162:165], v[222:225], v[76:79]
	v_mfma_f32_16x16x32_bf16 v[72:75], v[170:173], v[222:225], v[72:75]
	v_mfma_f32_16x16x32_bf16 v[60:63], v[162:165], v[230:233], v[60:63]
	v_mfma_f32_16x16x32_bf16 v[56:59], v[170:173], v[230:233], v[56:59]
	v_mfma_f32_16x16x32_bf16 v[92:95], v[166:169], v[210:213], v[92:95]
	v_mfma_f32_16x16x32_bf16 v[88:91], v[186:189], v[210:213], v[88:91]
	v_mfma_f32_16x16x32_bf16 v[84:87], v[166:169], v[218:221], v[84:87]
	v_mfma_f32_16x16x32_bf16 v[80:83], v[186:189], v[218:221], v[80:83]
	v_mfma_f32_16x16x32_bf16 v[76:79], v[166:169], v[226:229], v[76:79]
	v_mfma_f32_16x16x32_bf16 v[72:75], v[186:189], v[226:229], v[72:75]
	v_mfma_f32_16x16x32_bf16 v[60:63], v[166:169], v[242:245], v[60:63]
	v_mfma_f32_16x16x32_bf16 v[56:59], v[186:189], v[242:245], v[56:59]
	s_setprio 0
	s_setprio 1
	v_mfma_f32_16x16x32_bf16 v[28:31], v[190:193], v[206:209], v[28:31]
	v_mfma_f32_16x16x32_bf16 v[24:27], v[198:201], v[206:209], v[24:27]
	v_mfma_f32_16x16x32_bf16 v[20:23], v[190:193], v[214:217], v[20:23]
	v_mfma_f32_16x16x32_bf16 v[16:19], v[198:201], v[214:217], v[16:19]
	v_mfma_f32_16x16x32_bf16 v[12:15], v[190:193], v[222:225], v[12:15]
	v_mfma_f32_16x16x32_bf16 v[8:11], v[198:201], v[222:225], v[8:11]
	v_mfma_f32_16x16x32_bf16 v[4:7], v[190:193], v[230:233], v[4:7]
	v_mfma_f32_16x16x32_bf16 v[0:3], v[198:201], v[230:233], v[0:3]
	v_mfma_f32_16x16x32_bf16 v[28:31], v[194:197], v[210:213], v[28:31]
	v_mfma_f32_16x16x32_bf16 v[24:27], v[202:205], v[210:213], v[24:27]
	v_mfma_f32_16x16x32_bf16 v[20:23], v[194:197], v[218:221], v[20:23]
	v_mfma_f32_16x16x32_bf16 v[16:19], v[202:205], v[218:221], v[16:19]
	v_mfma_f32_16x16x32_bf16 v[12:15], v[194:197], v[226:229], v[12:15]
	v_mfma_f32_16x16x32_bf16 v[8:11], v[202:205], v[226:229], v[8:11]
	v_mfma_f32_16x16x32_bf16 v[4:7], v[194:197], v[242:245], v[4:7]
	v_mfma_f32_16x16x32_bf16 v[0:3], v[202:205], v[242:245], v[0:3]
	s_setprio 0
	s_barrier
	s_setprio 2
	s_add_i32 s57, 0, 0x18000
	v_add_u32_e32 v151, s57, v141
	s_add_i32 s58, 0, 0x1c000
	ds_read_b128 v[162:165], v151
	ds_read_b128 v[166:169], v151 offset:1024
	ds_read_b128 v[170:173], v151 offset:2048
	ds_read_b128 v[186:189], v151 offset:3072
	v_add_u32_e32 v151, s58, v141
	ds_read_b128 v[190:193], v151
	ds_read_b128 v[194:197], v151 offset:1024
	ds_read_b128 v[198:201], v151 offset:2048
	ds_read_b128 v[202:205], v151 offset:3072
	s_add_u32 s28, s28, 0x40000
	s_addc_u32 s29, s29, 0
	s_mov_b32 m0, s41
	v_lshl_add_u64 v[182:183], s[28:29], 0, v[134:135]
	ds_read_b128 v[206:209], v150 offset:32768
	ds_read_b128 v[210:213], v150 offset:33792
	ds_read_b128 v[214:217], v150 offset:34816
	ds_read_b128 v[218:221], v150 offset:35840
	ds_read_b128 v[222:225], v150 offset:36864
	ds_read_b128 v[226:229], v150 offset:37888
	ds_read_b128 v[230:233], v150 offset:38912
	ds_read_b128 v[242:245], v150 offset:39936
	global_load_lds_dwordx4 v[182:183], off
	v_lshl_add_u64 v[182:183], s[28:29], 0, v[132:133]
	s_mov_b32 m0, s42
	s_nop 0
	global_load_lds_dwordx4 v[182:183], off
	s_setprio 0
	s_waitcnt vmcnt(8)
	s_waitcnt lgkmcnt(0)
	s_barrier
	s_setprio 1
	v_mfma_f32_16x16x32_bf16 v[126:129], v[162:165], v[206:209], v[126:129]
	v_mfma_f32_16x16x32_bf16 v[122:125], v[170:173], v[206:209], v[122:125]
	v_mfma_f32_16x16x32_bf16 v[118:121], v[162:165], v[214:217], v[118:121]
	v_mfma_f32_16x16x32_bf16 v[114:117], v[170:173], v[214:217], v[114:117]
	v_mfma_f32_16x16x32_bf16 v[110:113], v[162:165], v[222:225], v[110:113]
	v_mfma_f32_16x16x32_bf16 v[106:109], v[170:173], v[222:225], v[106:109]
	v_mfma_f32_16x16x32_bf16 v[102:105], v[162:165], v[230:233], v[102:105]
	v_mfma_f32_16x16x32_bf16 v[98:101], v[170:173], v[230:233], v[98:101]
	v_mfma_f32_16x16x32_bf16 v[126:129], v[166:169], v[210:213], v[126:129]
	v_mfma_f32_16x16x32_bf16 v[122:125], v[186:189], v[210:213], v[122:125]
	v_mfma_f32_16x16x32_bf16 v[118:121], v[166:169], v[218:221], v[118:121]
	v_mfma_f32_16x16x32_bf16 v[114:117], v[186:189], v[218:221], v[114:117]
	v_mfma_f32_16x16x32_bf16 v[110:113], v[166:169], v[226:229], v[110:113]
	v_mfma_f32_16x16x32_bf16 v[106:109], v[186:189], v[226:229], v[106:109]
	v_mfma_f32_16x16x32_bf16 v[102:105], v[166:169], v[242:245], v[102:105]
	v_mfma_f32_16x16x32_bf16 v[98:101], v[186:189], v[242:245], v[98:101]
	s_setprio 0
	s_setprio 1
	v_mfma_f32_16x16x32_bf16 v[68:71], v[190:193], v[206:209], v[68:71]
	v_mfma_f32_16x16x32_bf16 v[64:67], v[198:201], v[206:209], v[64:67]
	v_mfma_f32_16x16x32_bf16 v[52:55], v[190:193], v[214:217], v[52:55]
	v_mfma_f32_16x16x32_bf16 v[48:51], v[198:201], v[214:217], v[48:51]
	v_mfma_f32_16x16x32_bf16 v[44:47], v[190:193], v[222:225], v[44:47]
	v_mfma_f32_16x16x32_bf16 v[40:43], v[198:201], v[222:225], v[40:43]
	v_mfma_f32_16x16x32_bf16 v[36:39], v[190:193], v[230:233], v[36:39]
	v_mfma_f32_16x16x32_bf16 v[32:35], v[198:201], v[230:233], v[32:35]
	v_mfma_f32_16x16x32_bf16 v[68:71], v[194:197], v[210:213], v[68:71]
	v_mfma_f32_16x16x32_bf16 v[64:67], v[202:205], v[210:213], v[64:67]
	v_mfma_f32_16x16x32_bf16 v[52:55], v[194:197], v[218:221], v[52:55]
	v_mfma_f32_16x16x32_bf16 v[48:51], v[202:205], v[218:221], v[48:51]
	v_mfma_f32_16x16x32_bf16 v[44:47], v[194:197], v[226:229], v[44:47]
	v_mfma_f32_16x16x32_bf16 v[40:43], v[202:205], v[226:229], v[40:43]
	v_mfma_f32_16x16x32_bf16 v[36:39], v[194:197], v[242:245], v[36:39]
	v_mfma_f32_16x16x32_bf16 v[32:35], v[202:205], v[242:245], v[32:35]
	s_setprio 0
	s_barrier
	s_setprio 2
	s_add_i32 s28, s57, s36
	v_lshl_add_u64 v[152:153], v[152:153], 0, s[16:17]
	s_mov_b32 m0, s28
	ds_read_b128 v[206:209], v150 offset:49152
	ds_read_b128 v[210:213], v150 offset:50176
	ds_read_b128 v[214:217], v150 offset:51200
	ds_read_b128 v[218:221], v150 offset:52224
	ds_read_b128 v[222:225], v150 offset:53248
	ds_read_b128 v[226:229], v150 offset:54272
	ds_read_b128 v[230:233], v150 offset:55296
	ds_read_b128 v[242:245], v150 offset:56320
	global_load_lds_dwordx4 v[152:153], off
	s_add_i32 m0, s28, 0x2000
	s_add_u32 s26, s26, 0x40080
	v_lshl_add_u64 v[152:153], v[154:155], 0, s[16:17]
	s_addc_u32 s27, s27, 0
	s_add_i32 s28, s58, s36
	global_load_lds_dwordx4 v[152:153], off
	v_lshl_add_u64 v[152:153], s[26:27], 0, v[96:97]
	s_mov_b32 m0, s28
	s_nop 0
	global_load_lds_dwordx4 v[152:153], off
	v_lshl_add_u64 v[152:153], s[26:27], 0, v[130:131]
	s_add_i32 m0, s28, 0x2000
	s_nop 0
	global_load_lds_dwordx4 v[152:153], off
	v_lshl_add_u64 v[152:153], v[156:157], 0, s[16:17]
	s_mov_b32 m0, s45
	s_nop 0
	global_load_lds_dwordx4 v[152:153], off
	v_lshl_add_u64 v[152:153], v[158:159], 0, s[16:17]
	s_mov_b32 m0, s46
	s_nop 0
	global_load_lds_dwordx4 v[152:153], off
	s_setprio 0
	s_waitcnt vmcnt(8)
	s_waitcnt lgkmcnt(0)
	s_barrier
	s_setprio 1
	v_mfma_f32_16x16x32_bf16 v[92:95], v[162:165], v[206:209], v[92:95]
	v_mfma_f32_16x16x32_bf16 v[88:91], v[170:173], v[206:209], v[88:91]
	v_mfma_f32_16x16x32_bf16 v[84:87], v[162:165], v[214:217], v[84:87]
	v_mfma_f32_16x16x32_bf16 v[80:83], v[170:173], v[214:217], v[80:83]
	v_mfma_f32_16x16x32_bf16 v[76:79], v[162:165], v[222:225], v[76:79]
	v_mfma_f32_16x16x32_bf16 v[72:75], v[170:173], v[222:225], v[72:75]
	v_mfma_f32_16x16x32_bf16 v[60:63], v[162:165], v[230:233], v[60:63]
	v_mfma_f32_16x16x32_bf16 v[56:59], v[170:173], v[230:233], v[56:59]
	v_mfma_f32_16x16x32_bf16 v[92:95], v[166:169], v[210:213], v[92:95]
	v_mfma_f32_16x16x32_bf16 v[88:91], v[186:189], v[210:213], v[88:91]
	v_mfma_f32_16x16x32_bf16 v[84:87], v[166:169], v[218:221], v[84:87]
	v_mfma_f32_16x16x32_bf16 v[80:83], v[186:189], v[218:221], v[80:83]
	v_mfma_f32_16x16x32_bf16 v[76:79], v[166:169], v[226:229], v[76:79]
	v_mfma_f32_16x16x32_bf16 v[72:75], v[186:189], v[226:229], v[72:75]
	v_mfma_f32_16x16x32_bf16 v[60:63], v[166:169], v[242:245], v[60:63]
	v_mfma_f32_16x16x32_bf16 v[56:59], v[186:189], v[242:245], v[56:59]
	s_setprio 0
	s_setprio 1
	v_mfma_f32_16x16x32_bf16 v[28:31], v[190:193], v[206:209], v[28:31]
	v_mfma_f32_16x16x32_bf16 v[24:27], v[198:201], v[206:209], v[24:27]
	v_mfma_f32_16x16x32_bf16 v[20:23], v[190:193], v[214:217], v[20:23]
	v_mfma_f32_16x16x32_bf16 v[16:19], v[198:201], v[214:217], v[16:19]
	v_mfma_f32_16x16x32_bf16 v[12:15], v[190:193], v[222:225], v[12:15]
	v_mfma_f32_16x16x32_bf16 v[8:11], v[198:201], v[222:225], v[8:11]
	v_mfma_f32_16x16x32_bf16 v[4:7], v[190:193], v[230:233], v[4:7]
	v_mfma_f32_16x16x32_bf16 v[0:3], v[198:201], v[230:233], v[0:3]
	v_mfma_f32_16x16x32_bf16 v[28:31], v[194:197], v[210:213], v[28:31]
	v_mfma_f32_16x16x32_bf16 v[24:27], v[202:205], v[210:213], v[24:27]
	v_mfma_f32_16x16x32_bf16 v[20:23], v[194:197], v[218:221], v[20:23]
	v_mfma_f32_16x16x32_bf16 v[16:19], v[202:205], v[218:221], v[16:19]
	v_mfma_f32_16x16x32_bf16 v[12:15], v[194:197], v[226:229], v[12:15]
	v_mfma_f32_16x16x32_bf16 v[8:11], v[202:205], v[226:229], v[8:11]
	v_mfma_f32_16x16x32_bf16 v[4:7], v[194:197], v[242:245], v[4:7]
	v_mfma_f32_16x16x32_bf16 v[0:3], v[202:205], v[242:245], v[0:3]
	s_setprio 0
	s_barrier
	s_setprio 2
	s_add_i32 s56, s56, 2
	s_add_u32 s14, s14, 0x100
	s_addc_u32 s15, s15, 0
	s_add_u32 s54, s54, 0x100
	s_addc_u32 s55, s55, 0
	s_cmp_gt_u32 s56, 13
	s_cbranch_scc0 .LBB0_393
	s_and_b64 vcc, exec, s[12:13]
	s_cbranch_vccz .LBB0_396
	s_barrier

.LBB0_427:
	s_add_u32 s14, s4, 0xfffc0080
	s_addc_u32 s15, s5, -1
	s_add_i32 s62, 0, 0x10000
	s_cmp_eq_u32 s61, 12
	s_cselect_b32 s37, s29, s15
	s_cselect_b32 s36, s57, s14
	v_add_u32_e32 v154, s62, v169
	s_cselect_b32 s15, s27, s60
	s_cselect_b32 s14, s58, s59
	s_add_i32 s64, 0, 0x14000
	ds_read_b128 v[142:145], v154
	ds_read_b128 v[146:149], v154 offset:1024
	ds_read_b128 v[150:153], v154 offset:2048
	ds_read_b128 v[162:165], v154 offset:3072
	v_add_u32_e32 v154, s64, v169
	ds_read_b128 v[186:189], v154
	ds_read_b128 v[190:193], v154 offset:1024
	ds_read_b128 v[194:197], v154 offset:2048
	ds_read_b128 v[198:201], v154 offset:3072
	v_lshl_add_u64 v[154:155], s[4:5], 0, v[138:139]
	s_add_i32 m0, s43, 0xc000
	ds_read_b128 v[202:205], v173
	ds_read_b128 v[206:209], v173 offset:1024
	ds_read_b128 v[210:213], v173 offset:2048
	ds_read_b128 v[214:217], v173 offset:3072
	ds_read_b128 v[218:221], v173 offset:4096
	ds_read_b128 v[222:225], v173 offset:5120
	ds_read_b128 v[226:229], v173 offset:6144
	ds_read_b128 v[230:233], v173 offset:7168
	global_load_lds_dwordx4 v[154:155], off
	v_lshl_add_u64 v[154:155], s[4:5], 0, v[140:141]
	s_add_i32 m0, s43, 0xe000
	s_nop 0
	global_load_lds_dwordx4 v[154:155], off
	s_setprio 0
	s_waitcnt vmcnt(8)
	s_waitcnt lgkmcnt(0)
	s_barrier
	s_setprio 1
	v_mfma_f32_16x16x32_bf16 v[126:129], v[142:145], v[202:205], v[126:129]
	v_mfma_f32_16x16x32_bf16 v[122:125], v[150:153], v[202:205], v[122:125]
	v_mfma_f32_16x16x32_bf16 v[110:113], v[142:145], v[210:213], v[110:113]
	v_mfma_f32_16x16x32_bf16 v[106:109], v[150:153], v[210:213], v[106:109]
	v_mfma_f32_16x16x32_bf16 v[92:95], v[142:145], v[218:221], v[92:95]
	v_mfma_f32_16x16x32_bf16 v[88:91], v[150:153], v[218:221], v[88:91]
	v_mfma_f32_16x16x32_bf16 v[76:79], v[142:145], v[226:229], v[76:79]
	v_mfma_f32_16x16x32_bf16 v[72:75], v[150:153], v[226:229], v[72:75]
	v_mfma_f32_16x16x32_bf16 v[126:129], v[146:149], v[206:209], v[126:129]
	v_mfma_f32_16x16x32_bf16 v[122:125], v[162:165], v[206:209], v[122:125]
	v_mfma_f32_16x16x32_bf16 v[110:113], v[146:149], v[214:217], v[110:113]
	v_mfma_f32_16x16x32_bf16 v[106:109], v[162:165], v[214:217], v[106:109]
	v_mfma_f32_16x16x32_bf16 v[92:95], v[146:149], v[222:225], v[92:95]
	v_mfma_f32_16x16x32_bf16 v[88:91], v[162:165], v[222:225], v[88:91]
	v_mfma_f32_16x16x32_bf16 v[76:79], v[146:149], v[230:233], v[76:79]
	v_mfma_f32_16x16x32_bf16 v[72:75], v[162:165], v[230:233], v[72:75]
	s_setprio 0
	s_setprio 1
	v_mfma_f32_16x16x32_bf16 v[118:121], v[186:189], v[202:205], v[118:121]
	v_mfma_f32_16x16x32_bf16 v[114:117], v[194:197], v[202:205], v[114:117]
	v_mfma_f32_16x16x32_bf16 v[102:105], v[186:189], v[210:213], v[102:105]
	v_mfma_f32_16x16x32_bf16 v[98:101], v[194:197], v[210:213], v[98:101]
	v_mfma_f32_16x16x32_bf16 v[84:87], v[186:189], v[218:221], v[84:87]
	v_mfma_f32_16x16x32_bf16 v[80:83], v[194:197], v[218:221], v[80:83]
	v_mfma_f32_16x16x32_bf16 v[68:71], v[186:189], v[226:229], v[68:71]
	v_mfma_f32_16x16x32_bf16 v[64:67], v[194:197], v[226:229], v[64:67]
	v_mfma_f32_16x16x32_bf16 v[118:121], v[190:193], v[206:209], v[118:121]
	v_mfma_f32_16x16x32_bf16 v[114:117], v[198:201], v[206:209], v[114:117]
	v_mfma_f32_16x16x32_bf16 v[102:105], v[190:193], v[214:217], v[102:105]
	v_mfma_f32_16x16x32_bf16 v[98:101], v[198:201], v[214:217], v[98:101]
	v_mfma_f32_16x16x32_bf16 v[84:87], v[190:193], v[222:225], v[84:87]
	v_mfma_f32_16x16x32_bf16 v[80:83], v[198:201], v[222:225], v[80:83]
	v_mfma_f32_16x16x32_bf16 v[68:71], v[190:193], v[230:233], v[68:71]
	v_mfma_f32_16x16x32_bf16 v[64:67], v[198:201], v[230:233], v[64:67]
	s_setprio 0
	s_barrier
	s_setprio 2
	s_add_i32 s62, s62, s42
	v_lshl_add_u64 v[154:155], s[14:15], 0, v[96:97]
	s_mov_b32 m0, s62
	ds_read_b128 v[202:205], v173 offset:16384
	ds_read_b128 v[206:209], v173 offset:17408
	ds_read_b128 v[210:213], v173 offset:18432
	ds_read_b128 v[214:217], v173 offset:19456
	ds_read_b128 v[218:221], v173 offset:20480
	ds_read_b128 v[222:225], v173 offset:21504
	ds_read_b128 v[226:229], v173 offset:22528
	ds_read_b128 v[230:233], v173 offset:23552
	global_load_lds_dwordx4 v[154:155], off
	s_add_i32 m0, s62, 0x2000
	s_add_u32 s62, s14, 0x40000
	v_lshl_add_u64 v[156:157], s[14:15], 0, v[130:131]
	s_addc_u32 s63, s15, 0
	s_add_i32 s64, s64, s42
	global_load_lds_dwordx4 v[156:157], off
	v_lshl_add_u64 v[158:159], s[62:63], 0, v[96:97]
	s_mov_b32 m0, s64
	v_lshl_add_u64 v[166:167], s[36:37], 0, v[132:133]
	global_load_lds_dwordx4 v[158:159], off
	v_lshl_add_u64 v[158:159], s[62:63], 0, v[130:131]
	s_add_i32 m0, s64, 0x2000
	s_nop 0
	global_load_lds_dwordx4 v[158:159], off
	v_lshl_add_u64 v[158:159], s[36:37], 0, v[134:135]
	s_mov_b32 m0, s43
	s_nop 0
	global_load_lds_dwordx4 v[158:159], off
	s_mov_b32 m0, s44
	s_nop 0
	global_load_lds_dwordx4 v[166:167], off
	s_setprio 0
	s_waitcnt vmcnt(8)
	s_waitcnt lgkmcnt(0)
	s_barrier
	s_setprio 1
	v_mfma_f32_16x16x32_bf16 v[60:63], v[142:145], v[202:205], v[60:63]
	v_mfma_f32_16x16x32_bf16 v[56:59], v[150:153], v[202:205], v[56:59]
	v_mfma_f32_16x16x32_bf16 v[44:47], v[142:145], v[210:213], v[44:47]
	v_mfma_f32_16x16x32_bf16 v[40:43], v[150:153], v[210:213], v[40:43]
	v_mfma_f32_16x16x32_bf16 v[28:31], v[142:145], v[218:221], v[28:31]
	v_mfma_f32_16x16x32_bf16 v[24:27], v[150:153], v[218:221], v[24:27]
	v_mfma_f32_16x16x32_bf16 v[12:15], v[142:145], v[226:229], v[12:15]
	v_mfma_f32_16x16x32_bf16 v[8:11], v[150:153], v[226:229], v[8:11]
	v_mfma_f32_16x16x32_bf16 v[60:63], v[146:149], v[206:209], v[60:63]
	v_mfma_f32_16x16x32_bf16 v[56:59], v[162:165], v[206:209], v[56:59]
	v_mfma_f32_16x16x32_bf16 v[44:47], v[146:149], v[214:217], v[44:47]
	v_mfma_f32_16x16x32_bf16 v[40:43], v[162:165], v[214:217], v[40:43]
	v_mfma_f32_16x16x32_bf16 v[28:31], v[146:149], v[222:225], v[28:31]
	v_mfma_f32_16x16x32_bf16 v[24:27], v[162:165], v[222:225], v[24:27]
	v_mfma_f32_16x16x32_bf16 v[12:15], v[146:149], v[230:233], v[12:15]
	v_mfma_f32_16x16x32_bf16 v[8:11], v[162:165], v[230:233], v[8:11]
	s_setprio 0
	s_setprio 1
	v_mfma_f32_16x16x32_bf16 v[52:55], v[186:189], v[202:205], v[52:55]
	v_mfma_f32_16x16x32_bf16 v[48:51], v[194:197], v[202:205], v[48:51]
	v_mfma_f32_16x16x32_bf16 v[36:39], v[186:189], v[210:213], v[36:39]
	v_mfma_f32_16x16x32_bf16 v[32:35], v[194:197], v[210:213], v[32:35]
	v_mfma_f32_16x16x32_bf16 v[20:23], v[186:189], v[218:221], v[20:23]
	v_mfma_f32_16x16x32_bf16 v[16:19], v[194:197], v[218:221], v[16:19]
	v_mfma_f32_16x16x32_bf16 v[4:7], v[186:189], v[226:229], v[4:7]
	v_mfma_f32_16x16x32_bf16 v[0:3], v[194:197], v[226:229], v[0:3]
	v_mfma_f32_16x16x32_bf16 v[52:55], v[190:193], v[206:209], v[52:55]
	v_mfma_f32_16x16x32_bf16 v[48:51], v[198:201], v[206:209], v[48:51]
	v_mfma_f32_16x16x32_bf16 v[36:39], v[190:193], v[214:217], v[36:39]
	v_mfma_f32_16x16x32_bf16 v[32:35], v[198:201], v[214:217], v[32:35]
	v_mfma_f32_16x16x32_bf16 v[20:23], v[190:193], v[222:225], v[20:23]
	v_mfma_f32_16x16x32_bf16 v[16:19], v[198:201], v[222:225], v[16:19]
	v_mfma_f32_16x16x32_bf16 v[4:7], v[190:193], v[230:233], v[4:7]
	v_mfma_f32_16x16x32_bf16 v[0:3], v[198:201], v[230:233], v[0:3]
	s_setprio 0
	s_barrier
	s_setprio 2
	s_add_i32 s62, 0, 0x18000
	s_add_i32 s63, 0, 0x1c000
	v_add_u32_e32 v162, s62, v169
	v_add_u32_e32 v182, s63, v169
	ds_read_b128 v[142:145], v162
	ds_read_b128 v[146:149], v162 offset:1024
	ds_read_b128 v[150:153], v162 offset:2048
	ds_read_b128 v[162:165], v162 offset:3072
	ds_read_b128 v[186:189], v182
	ds_read_b128 v[190:193], v182 offset:1024
	ds_read_b128 v[194:197], v182 offset:2048
	ds_read_b128 v[198:201], v182 offset:3072
	s_add_u32 s36, s36, 0x40000
	s_addc_u32 s37, s37, 0
	s_mov_b32 m0, s45
	v_lshl_add_u64 v[182:183], s[36:37], 0, v[134:135]
	ds_read_b128 v[202:205], v173 offset:32768
	ds_read_b128 v[206:209], v173 offset:33792
	ds_read_b128 v[210:213], v173 offset:34816
	ds_read_b128 v[214:217], v173 offset:35840
	ds_read_b128 v[218:221], v173 offset:36864
	ds_read_b128 v[222:225], v173 offset:37888
	ds_read_b128 v[226:229], v173 offset:38912
	ds_read_b128 v[230:233], v173 offset:39936
	global_load_lds_dwordx4 v[182:183], off
	v_lshl_add_u64 v[182:183], s[36:37], 0, v[132:133]
	s_mov_b32 m0, s46
	s_nop 0
	global_load_lds_dwordx4 v[182:183], off
	s_setprio 0
	s_waitcnt vmcnt(8)
	s_waitcnt lgkmcnt(0)
	s_barrier
	s_setprio 1
	v_mfma_f32_16x16x32_bf16 v[126:129], v[142:145], v[202:205], v[126:129]
	v_mfma_f32_16x16x32_bf16 v[122:125], v[150:153], v[202:205], v[122:125]
	v_mfma_f32_16x16x32_bf16 v[110:113], v[142:145], v[210:213], v[110:113]
	v_mfma_f32_16x16x32_bf16 v[106:109], v[150:153], v[210:213], v[106:109]
	v_mfma_f32_16x16x32_bf16 v[92:95], v[142:145], v[218:221], v[92:95]
	v_mfma_f32_16x16x32_bf16 v[88:91], v[150:153], v[218:221], v[88:91]
	v_mfma_f32_16x16x32_bf16 v[76:79], v[142:145], v[226:229], v[76:79]
	v_mfma_f32_16x16x32_bf16 v[72:75], v[150:153], v[226:229], v[72:75]
	v_mfma_f32_16x16x32_bf16 v[126:129], v[146:149], v[206:209], v[126:129]
	v_mfma_f32_16x16x32_bf16 v[122:125], v[162:165], v[206:209], v[122:125]
	v_mfma_f32_16x16x32_bf16 v[110:113], v[146:149], v[214:217], v[110:113]
	v_mfma_f32_16x16x32_bf16 v[106:109], v[162:165], v[214:217], v[106:109]
	v_mfma_f32_16x16x32_bf16 v[92:95], v[146:149], v[222:225], v[92:95]
	v_mfma_f32_16x16x32_bf16 v[88:91], v[162:165], v[222:225], v[88:91]
	v_mfma_f32_16x16x32_bf16 v[76:79], v[146:149], v[230:233], v[76:79]
	v_mfma_f32_16x16x32_bf16 v[72:75], v[162:165], v[230:233], v[72:75]
	s_setprio 0
	s_setprio 1
	v_mfma_f32_16x16x32_bf16 v[118:121], v[186:189], v[202:205], v[118:121]
	v_mfma_f32_16x16x32_bf16 v[114:117], v[194:197], v[202:205], v[114:117]
	v_mfma_f32_16x16x32_bf16 v[102:105], v[186:189], v[210:213], v[102:105]
	v_mfma_f32_16x16x32_bf16 v[98:101], v[194:197], v[210:213], v[98:101]
	v_mfma_f32_16x16x32_bf16 v[84:87], v[186:189], v[218:221], v[84:87]
	v_mfma_f32_16x16x32_bf16 v[80:83], v[194:197], v[218:221], v[80:83]
	v_mfma_f32_16x16x32_bf16 v[68:71], v[186:189], v[226:229], v[68:71]
	v_mfma_f32_16x16x32_bf16 v[64:67], v[194:197], v[226:229], v[64:67]
	v_mfma_f32_16x16x32_bf16 v[118:121], v[190:193], v[206:209], v[118:121]
	v_mfma_f32_16x16x32_bf16 v[114:117], v[198:201], v[206:209], v[114:117]
	v_mfma_f32_16x16x32_bf16 v[102:105], v[190:193], v[214:217], v[102:105]
	v_mfma_f32_16x16x32_bf16 v[98:101], v[198:201], v[214:217], v[98:101]
	v_mfma_f32_16x16x32_bf16 v[84:87], v[190:193], v[222:225], v[84:87]
	v_mfma_f32_16x16x32_bf16 v[80:83], v[198:201], v[222:225], v[80:83]
	v_mfma_f32_16x16x32_bf16 v[68:71], v[190:193], v[230:233], v[68:71]
	v_mfma_f32_16x16x32_bf16 v[64:67], v[198:201], v[230:233], v[64:67]
	s_setprio 0
	s_barrier
	s_setprio 2
	s_add_i32 s36, s62, s42
	v_lshl_add_u64 v[154:155], v[154:155], 0, s[16:17]
	s_mov_b32 m0, s36
	ds_read_b128 v[202:205], v173 offset:49152
	ds_read_b128 v[206:209], v173 offset:50176
	ds_read_b128 v[210:213], v173 offset:51200
	ds_read_b128 v[214:217], v173 offset:52224
	ds_read_b128 v[218:221], v173 offset:53248
	ds_read_b128 v[222:225], v173 offset:54272
	ds_read_b128 v[226:229], v173 offset:55296
	ds_read_b128 v[230:233], v173 offset:56320
	global_load_lds_dwordx4 v[154:155], off
	s_add_i32 m0, s36, 0x2000
	s_add_u32 s14, s14, 0x40080
	v_lshl_add_u64 v[154:155], v[156:157], 0, s[16:17]
	s_addc_u32 s15, s15, 0
	s_add_i32 s36, s63, s42
	global_load_lds_dwordx4 v[154:155], off
	v_lshl_add_u64 v[154:155], s[14:15], 0, v[96:97]
	s_mov_b32 m0, s36
	s_nop 0
	global_load_lds_dwordx4 v[154:155], off
	v_lshl_add_u64 v[154:155], s[14:15], 0, v[130:131]
	s_add_i32 m0, s36, 0x2000
	s_nop 0
	global_load_lds_dwordx4 v[154:155], off
	v_lshl_add_u64 v[154:155], v[158:159], 0, s[16:17]
	s_mov_b32 m0, s52
	s_nop 0
	global_load_lds_dwordx4 v[154:155], off
	v_lshl_add_u64 v[154:155], v[166:167], 0, s[16:17]
	s_mov_b32 m0, s53
	s_nop 0
	global_load_lds_dwordx4 v[154:155], off
	s_setprio 0
	s_waitcnt vmcnt(8)
	s_waitcnt lgkmcnt(0)
	s_barrier
	s_setprio 1
	v_mfma_f32_16x16x32_bf16 v[60:63], v[142:145], v[202:205], v[60:63]
	v_mfma_f32_16x16x32_bf16 v[56:59], v[150:153], v[202:205], v[56:59]
	v_mfma_f32_16x16x32_bf16 v[44:47], v[142:145], v[210:213], v[44:47]
	v_mfma_f32_16x16x32_bf16 v[40:43], v[150:153], v[210:213], v[40:43]
	v_mfma_f32_16x16x32_bf16 v[28:31], v[142:145], v[218:221], v[28:31]
	v_mfma_f32_16x16x32_bf16 v[24:27], v[150:153], v[218:221], v[24:27]
	v_mfma_f32_16x16x32_bf16 v[12:15], v[142:145], v[226:229], v[12:15]
	v_mfma_f32_16x16x32_bf16 v[8:11], v[150:153], v[226:229], v[8:11]
	v_mfma_f32_16x16x32_bf16 v[60:63], v[146:149], v[206:209], v[60:63]
	v_mfma_f32_16x16x32_bf16 v[56:59], v[162:165], v[206:209], v[56:59]
	v_mfma_f32_16x16x32_bf16 v[44:47], v[146:149], v[214:217], v[44:47]
	v_mfma_f32_16x16x32_bf16 v[40:43], v[162:165], v[214:217], v[40:43]
	v_mfma_f32_16x16x32_bf16 v[28:31], v[146:149], v[222:225], v[28:31]
	v_mfma_f32_16x16x32_bf16 v[24:27], v[162:165], v[222:225], v[24:27]
	v_mfma_f32_16x16x32_bf16 v[12:15], v[146:149], v[230:233], v[12:15]
	v_mfma_f32_16x16x32_bf16 v[8:11], v[162:165], v[230:233], v[8:11]
	s_setprio 0
	s_setprio 1
	v_mfma_f32_16x16x32_bf16 v[52:55], v[186:189], v[202:205], v[52:55]
	v_mfma_f32_16x16x32_bf16 v[48:51], v[194:197], v[202:205], v[48:51]
	v_mfma_f32_16x16x32_bf16 v[36:39], v[186:189], v[210:213], v[36:39]
	v_mfma_f32_16x16x32_bf16 v[32:35], v[194:197], v[210:213], v[32:35]
	v_mfma_f32_16x16x32_bf16 v[20:23], v[186:189], v[218:221], v[20:23]
	v_mfma_f32_16x16x32_bf16 v[16:19], v[194:197], v[218:221], v[16:19]
	v_mfma_f32_16x16x32_bf16 v[4:7], v[186:189], v[226:229], v[4:7]
	v_mfma_f32_16x16x32_bf16 v[0:3], v[194:197], v[226:229], v[0:3]
	v_mfma_f32_16x16x32_bf16 v[52:55], v[190:193], v[206:209], v[52:55]
	v_mfma_f32_16x16x32_bf16 v[48:51], v[198:201], v[206:209], v[48:51]
	v_mfma_f32_16x16x32_bf16 v[36:39], v[190:193], v[214:217], v[36:39]
	v_mfma_f32_16x16x32_bf16 v[32:35], v[198:201], v[214:217], v[32:35]
	v_mfma_f32_16x16x32_bf16 v[20:23], v[190:193], v[222:225], v[20:23]
	v_mfma_f32_16x16x32_bf16 v[16:19], v[198:201], v[222:225], v[16:19]
	v_mfma_f32_16x16x32_bf16 v[4:7], v[190:193], v[230:233], v[4:7]
	v_mfma_f32_16x16x32_bf16 v[0:3], v[198:201], v[230:233], v[0:3]
	s_setprio 0
	s_barrier
	s_setprio 2
	s_add_i32 s61, s61, 2
	s_add_u32 s4, s4, 0x100
	s_addc_u32 s5, s5, 0
	s_add_u32 s59, s59, 0x100
	s_addc_u32 s60, s60, 0
	s_cmp_gt_u32 s61, 13
	s_cbranch_scc0 .LBB0_427
	s_and_b64 vcc, exec, s[24:25]
	s_cbranch_vccz .LBB0_430
	s_barrier

.LBB0_449:
	s_add_u32 s30, s14, 0xfffc0080
	s_addc_u32 s31, s15, -1
	s_add_i32 s60, 0, 0x10000
	s_cmp_eq_u32 s59, 12
	s_cselect_b32 s35, s25, s31
	s_cselect_b32 s34, s55, s30
	v_add_u32_e32 v96, s60, v151
	s_cselect_b32 s31, s13, s58
	s_cselect_b32 s30, s56, s57
	s_add_i32 s62, 0, 0x14000
	ds_read_b128 v[144:147], v96
	ds_read_b128 v[164:167], v96 offset:1024
	ds_read_b128 v[168:171], v96 offset:2048
	ds_read_b128 v[186:189], v96 offset:3072
	v_add_u32_e32 v96, s62, v151
	ds_read_b128 v[190:193], v96
	ds_read_b128 v[194:197], v96 offset:1024
	ds_read_b128 v[198:201], v96 offset:2048
	ds_read_b128 v[202:205], v96 offset:3072
	v_lshl_add_u64 v[148:149], s[14:15], 0, v[140:141]
	s_add_i32 m0, s41, 0xc000
	ds_read_b128 v[206:209], v163
	ds_read_b128 v[210:213], v163 offset:1024
	ds_read_b128 v[214:217], v163 offset:2048
	ds_read_b128 v[218:221], v163 offset:3072
	ds_read_b128 v[222:225], v163 offset:4096
	ds_read_b128 v[226:229], v163 offset:5120
	ds_read_b128 v[230:233], v163 offset:6144
	ds_read_b128 v[242:245], v163 offset:7168
	global_load_lds_dwordx4 v[148:149], off
	v_lshl_add_u64 v[148:149], s[14:15], 0, v[142:143]
	s_add_i32 m0, s41, 0xe000
	s_nop 0
	global_load_lds_dwordx4 v[148:149], off
	s_setprio 0
	s_waitcnt vmcnt(8)
	s_waitcnt lgkmcnt(0)
	s_barrier
	s_setprio 1
	v_mfma_f32_16x16x32_bf16 v[126:129], v[144:147], v[206:209], v[126:129]
	v_mfma_f32_16x16x32_bf16 v[122:125], v[168:171], v[206:209], v[122:125]
	v_mfma_f32_16x16x32_bf16 v[110:113], v[144:147], v[214:217], v[110:113]
	v_mfma_f32_16x16x32_bf16 v[106:109], v[168:171], v[214:217], v[106:109]
	v_mfma_f32_16x16x32_bf16 v[92:95], v[144:147], v[222:225], v[92:95]
	v_mfma_f32_16x16x32_bf16 v[88:91], v[168:171], v[222:225], v[88:91]
	v_mfma_f32_16x16x32_bf16 v[76:79], v[144:147], v[230:233], v[76:79]
	v_mfma_f32_16x16x32_bf16 v[72:75], v[168:171], v[230:233], v[72:75]
	v_mfma_f32_16x16x32_bf16 v[126:129], v[164:167], v[210:213], v[126:129]
	v_mfma_f32_16x16x32_bf16 v[122:125], v[186:189], v[210:213], v[122:125]
	v_mfma_f32_16x16x32_bf16 v[110:113], v[164:167], v[218:221], v[110:113]
	v_mfma_f32_16x16x32_bf16 v[106:109], v[186:189], v[218:221], v[106:109]
	v_mfma_f32_16x16x32_bf16 v[92:95], v[164:167], v[226:229], v[92:95]
	v_mfma_f32_16x16x32_bf16 v[88:91], v[186:189], v[226:229], v[88:91]
	v_mfma_f32_16x16x32_bf16 v[76:79], v[164:167], v[242:245], v[76:79]
	v_mfma_f32_16x16x32_bf16 v[72:75], v[186:189], v[242:245], v[72:75]
	s_setprio 0
	s_setprio 1
	v_mfma_f32_16x16x32_bf16 v[118:121], v[190:193], v[206:209], v[118:121]
	v_mfma_f32_16x16x32_bf16 v[114:117], v[198:201], v[206:209], v[114:117]
	v_mfma_f32_16x16x32_bf16 v[102:105], v[190:193], v[214:217], v[102:105]
	v_mfma_f32_16x16x32_bf16 v[98:101], v[198:201], v[214:217], v[98:101]
	v_mfma_f32_16x16x32_bf16 v[84:87], v[190:193], v[222:225], v[84:87]
	v_mfma_f32_16x16x32_bf16 v[80:83], v[198:201], v[222:225], v[80:83]
	v_mfma_f32_16x16x32_bf16 v[68:71], v[190:193], v[230:233], v[68:71]
	v_mfma_f32_16x16x32_bf16 v[64:67], v[198:201], v[230:233], v[64:67]
	v_mfma_f32_16x16x32_bf16 v[118:121], v[194:197], v[210:213], v[118:121]
	v_mfma_f32_16x16x32_bf16 v[114:117], v[202:205], v[210:213], v[114:117]
	v_mfma_f32_16x16x32_bf16 v[102:105], v[194:197], v[218:221], v[102:105]
	v_mfma_f32_16x16x32_bf16 v[98:101], v[202:205], v[218:221], v[98:101]
	v_mfma_f32_16x16x32_bf16 v[84:87], v[194:197], v[226:229], v[84:87]
	v_mfma_f32_16x16x32_bf16 v[80:83], v[202:205], v[226:229], v[80:83]
	v_mfma_f32_16x16x32_bf16 v[68:71], v[194:197], v[242:245], v[68:71]
	v_mfma_f32_16x16x32_bf16 v[64:67], v[202:205], v[242:245], v[64:67]
	s_setprio 0
	s_barrier
	s_setprio 2
	s_add_i32 s60, s60, s40
	v_lshl_add_u64 v[148:149], s[30:31], 0, v[134:135]
	s_mov_b32 m0, s60
	ds_read_b128 v[206:209], v163 offset:16384
	ds_read_b128 v[210:213], v163 offset:17408
	ds_read_b128 v[214:217], v163 offset:18432
	ds_read_b128 v[218:221], v163 offset:19456
	ds_read_b128 v[222:225], v163 offset:20480
	ds_read_b128 v[226:229], v163 offset:21504
	ds_read_b128 v[230:233], v163 offset:22528
	ds_read_b128 v[242:245], v163 offset:23552
	global_load_lds_dwordx4 v[148:149], off
	s_add_i32 m0, s60, 0x2000
	s_add_u32 s60, s30, 0x40000
	v_lshl_add_u64 v[154:155], s[30:31], 0, v[130:131]
	s_addc_u32 s61, s31, 0
	s_add_i32 s62, s62, s40
	global_load_lds_dwordx4 v[154:155], off
	v_lshl_add_u64 v[156:157], s[60:61], 0, v[134:135]
	s_mov_b32 m0, s62
	v_lshl_add_u64 v[158:159], s[34:35], 0, v[132:133]
	global_load_lds_dwordx4 v[156:157], off
	v_lshl_add_u64 v[156:157], s[60:61], 0, v[130:131]
	s_add_i32 m0, s62, 0x2000
	s_nop 0
	global_load_lds_dwordx4 v[156:157], off
	v_lshl_add_u64 v[156:157], s[34:35], 0, v[136:137]
	s_mov_b32 m0, s41
	s_nop 0
	global_load_lds_dwordx4 v[156:157], off
	s_mov_b32 m0, s42
	s_nop 0
	global_load_lds_dwordx4 v[158:159], off
	s_setprio 0
	s_waitcnt vmcnt(8)
	s_waitcnt lgkmcnt(0)
	s_barrier
	s_setprio 1
	v_mfma_f32_16x16x32_bf16 v[60:63], v[144:147], v[206:209], v[60:63]
	v_mfma_f32_16x16x32_bf16 v[56:59], v[168:171], v[206:209], v[56:59]
	v_mfma_f32_16x16x32_bf16 v[44:47], v[144:147], v[214:217], v[44:47]
	v_mfma_f32_16x16x32_bf16 v[40:43], v[168:171], v[214:217], v[40:43]
	v_mfma_f32_16x16x32_bf16 v[28:31], v[144:147], v[222:225], v[28:31]
	v_mfma_f32_16x16x32_bf16 v[24:27], v[168:171], v[222:225], v[24:27]
	v_mfma_f32_16x16x32_bf16 v[12:15], v[144:147], v[230:233], v[12:15]
	v_mfma_f32_16x16x32_bf16 v[8:11], v[168:171], v[230:233], v[8:11]
	v_mfma_f32_16x16x32_bf16 v[60:63], v[164:167], v[210:213], v[60:63]
	v_mfma_f32_16x16x32_bf16 v[56:59], v[186:189], v[210:213], v[56:59]
	v_mfma_f32_16x16x32_bf16 v[44:47], v[164:167], v[218:221], v[44:47]
	v_mfma_f32_16x16x32_bf16 v[40:43], v[186:189], v[218:221], v[40:43]
	v_mfma_f32_16x16x32_bf16 v[28:31], v[164:167], v[226:229], v[28:31]
	v_mfma_f32_16x16x32_bf16 v[24:27], v[186:189], v[226:229], v[24:27]
	v_mfma_f32_16x16x32_bf16 v[12:15], v[164:167], v[242:245], v[12:15]
	v_mfma_f32_16x16x32_bf16 v[8:11], v[186:189], v[242:245], v[8:11]
	s_setprio 0
	s_setprio 1
	v_mfma_f32_16x16x32_bf16 v[52:55], v[190:193], v[206:209], v[52:55]
	v_mfma_f32_16x16x32_bf16 v[48:51], v[198:201], v[206:209], v[48:51]
	v_mfma_f32_16x16x32_bf16 v[36:39], v[190:193], v[214:217], v[36:39]
	v_mfma_f32_16x16x32_bf16 v[32:35], v[198:201], v[214:217], v[32:35]
	v_mfma_f32_16x16x32_bf16 v[20:23], v[190:193], v[222:225], v[20:23]
	v_mfma_f32_16x16x32_bf16 v[16:19], v[198:201], v[222:225], v[16:19]
	v_mfma_f32_16x16x32_bf16 v[4:7], v[190:193], v[230:233], v[4:7]
	v_mfma_f32_16x16x32_bf16 v[0:3], v[198:201], v[230:233], v[0:3]
	v_mfma_f32_16x16x32_bf16 v[52:55], v[194:197], v[210:213], v[52:55]
	v_mfma_f32_16x16x32_bf16 v[48:51], v[202:205], v[210:213], v[48:51]
	v_mfma_f32_16x16x32_bf16 v[36:39], v[194:197], v[218:221], v[36:39]
	v_mfma_f32_16x16x32_bf16 v[32:35], v[202:205], v[218:221], v[32:35]
	v_mfma_f32_16x16x32_bf16 v[20:23], v[194:197], v[226:229], v[20:23]
	v_mfma_f32_16x16x32_bf16 v[16:19], v[202:205], v[226:229], v[16:19]
	v_mfma_f32_16x16x32_bf16 v[4:7], v[194:197], v[242:245], v[4:7]
	v_mfma_f32_16x16x32_bf16 v[0:3], v[202:205], v[242:245], v[0:3]
	s_setprio 0
	s_barrier
	s_setprio 2
	s_add_i32 s60, 0, 0x18000
	v_add_u32_e32 v96, s60, v151
	s_add_i32 s61, 0, 0x1c000
	ds_read_b128 v[144:147], v96
	ds_read_b128 v[164:167], v96 offset:1024
	ds_read_b128 v[168:171], v96 offset:2048
	ds_read_b128 v[186:189], v96 offset:3072
	v_add_u32_e32 v96, s61, v151
	ds_read_b128 v[190:193], v96
	ds_read_b128 v[194:197], v96 offset:1024
	ds_read_b128 v[198:201], v96 offset:2048
	ds_read_b128 v[202:205], v96 offset:3072
	s_add_u32 s34, s34, 0x40000
	s_addc_u32 s35, s35, 0
	s_mov_b32 m0, s43
	v_lshl_add_u64 v[172:173], s[34:35], 0, v[136:137]
	ds_read_b128 v[206:209], v163 offset:32768
	ds_read_b128 v[210:213], v163 offset:33792
	ds_read_b128 v[214:217], v163 offset:34816
	ds_read_b128 v[218:221], v163 offset:35840
	ds_read_b128 v[222:225], v163 offset:36864
	ds_read_b128 v[226:229], v163 offset:37888
	ds_read_b128 v[230:233], v163 offset:38912
	ds_read_b128 v[242:245], v163 offset:39936
	global_load_lds_dwordx4 v[172:173], off
	v_lshl_add_u64 v[172:173], s[34:35], 0, v[132:133]
	s_mov_b32 m0, s44
	s_nop 0
	global_load_lds_dwordx4 v[172:173], off
	s_setprio 0
	s_waitcnt vmcnt(8)
	s_waitcnt lgkmcnt(0)
	s_barrier
	s_setprio 1
	v_mfma_f32_16x16x32_bf16 v[126:129], v[144:147], v[206:209], v[126:129]
	v_mfma_f32_16x16x32_bf16 v[122:125], v[168:171], v[206:209], v[122:125]
	v_mfma_f32_16x16x32_bf16 v[110:113], v[144:147], v[214:217], v[110:113]
	v_mfma_f32_16x16x32_bf16 v[106:109], v[168:171], v[214:217], v[106:109]
	v_mfma_f32_16x16x32_bf16 v[92:95], v[144:147], v[222:225], v[92:95]
	v_mfma_f32_16x16x32_bf16 v[88:91], v[168:171], v[222:225], v[88:91]
	v_mfma_f32_16x16x32_bf16 v[76:79], v[144:147], v[230:233], v[76:79]
	v_mfma_f32_16x16x32_bf16 v[72:75], v[168:171], v[230:233], v[72:75]
	v_mfma_f32_16x16x32_bf16 v[126:129], v[164:167], v[210:213], v[126:129]
	v_mfma_f32_16x16x32_bf16 v[122:125], v[186:189], v[210:213], v[122:125]
	v_mfma_f32_16x16x32_bf16 v[110:113], v[164:167], v[218:221], v[110:113]
	v_mfma_f32_16x16x32_bf16 v[106:109], v[186:189], v[218:221], v[106:109]
	v_mfma_f32_16x16x32_bf16 v[92:95], v[164:167], v[226:229], v[92:95]
	v_mfma_f32_16x16x32_bf16 v[88:91], v[186:189], v[226:229], v[88:91]
	v_mfma_f32_16x16x32_bf16 v[76:79], v[164:167], v[242:245], v[76:79]
	v_mfma_f32_16x16x32_bf16 v[72:75], v[186:189], v[242:245], v[72:75]
	s_setprio 0
	s_setprio 1
	v_mfma_f32_16x16x32_bf16 v[118:121], v[190:193], v[206:209], v[118:121]
	v_mfma_f32_16x16x32_bf16 v[114:117], v[198:201], v[206:209], v[114:117]
	v_mfma_f32_16x16x32_bf16 v[102:105], v[190:193], v[214:217], v[102:105]
	v_mfma_f32_16x16x32_bf16 v[98:101], v[198:201], v[214:217], v[98:101]
	v_mfma_f32_16x16x32_bf16 v[84:87], v[190:193], v[222:225], v[84:87]
	v_mfma_f32_16x16x32_bf16 v[80:83], v[198:201], v[222:225], v[80:83]
	v_mfma_f32_16x16x32_bf16 v[68:71], v[190:193], v[230:233], v[68:71]
	v_mfma_f32_16x16x32_bf16 v[64:67], v[198:201], v[230:233], v[64:67]
	v_mfma_f32_16x16x32_bf16 v[118:121], v[194:197], v[210:213], v[118:121]
	v_mfma_f32_16x16x32_bf16 v[114:117], v[202:205], v[210:213], v[114:117]
	v_mfma_f32_16x16x32_bf16 v[102:105], v[194:197], v[218:221], v[102:105]
	v_mfma_f32_16x16x32_bf16 v[98:101], v[202:205], v[218:221], v[98:101]
	v_mfma_f32_16x16x32_bf16 v[84:87], v[194:197], v[226:229], v[84:87]
	v_mfma_f32_16x16x32_bf16 v[80:83], v[202:205], v[226:229], v[80:83]
	v_mfma_f32_16x16x32_bf16 v[68:71], v[194:197], v[242:245], v[68:71]
	v_mfma_f32_16x16x32_bf16 v[64:67], v[202:205], v[242:245], v[64:67]
	s_setprio 0
	s_barrier
	s_setprio 2
	s_add_i32 s34, s60, s40
	v_lshl_add_u64 v[148:149], v[148:149], 0, s[16:17]
	s_mov_b32 m0, s34
	ds_read_b128 v[206:209], v163 offset:49152
	ds_read_b128 v[210:213], v163 offset:50176
	ds_read_b128 v[214:217], v163 offset:51200
	ds_read_b128 v[218:221], v163 offset:52224
	ds_read_b128 v[222:225], v163 offset:53248
	ds_read_b128 v[226:229], v163 offset:54272
	ds_read_b128 v[230:233], v163 offset:55296
	ds_read_b128 v[242:245], v163 offset:56320
	global_load_lds_dwordx4 v[148:149], off
	s_add_i32 m0, s34, 0x2000
	s_add_u32 s30, s30, 0x40080
	v_lshl_add_u64 v[148:149], v[154:155], 0, s[16:17]
	s_addc_u32 s31, s31, 0
	s_add_i32 s34, s61, s40
	global_load_lds_dwordx4 v[148:149], off
	v_lshl_add_u64 v[148:149], s[30:31], 0, v[134:135]
	s_mov_b32 m0, s34
	s_nop 0
	global_load_lds_dwordx4 v[148:149], off
	v_lshl_add_u64 v[148:149], s[30:31], 0, v[130:131]
	s_add_i32 m0, s34, 0x2000
	s_nop 0
	global_load_lds_dwordx4 v[148:149], off
	v_lshl_add_u64 v[148:149], v[156:157], 0, s[16:17]
	s_mov_b32 m0, s49
	s_nop 0
	global_load_lds_dwordx4 v[148:149], off
	v_lshl_add_u64 v[148:149], v[158:159], 0, s[16:17]
	s_mov_b32 m0, s50
	s_nop 0
	global_load_lds_dwordx4 v[148:149], off
	s_setprio 0
	s_waitcnt vmcnt(8)
	s_waitcnt lgkmcnt(0)
	s_barrier
	s_setprio 1
	v_mfma_f32_16x16x32_bf16 v[60:63], v[144:147], v[206:209], v[60:63]
	v_mfma_f32_16x16x32_bf16 v[56:59], v[168:171], v[206:209], v[56:59]
	v_mfma_f32_16x16x32_bf16 v[44:47], v[144:147], v[214:217], v[44:47]
	v_mfma_f32_16x16x32_bf16 v[40:43], v[168:171], v[214:217], v[40:43]
	v_mfma_f32_16x16x32_bf16 v[28:31], v[144:147], v[222:225], v[28:31]
	v_mfma_f32_16x16x32_bf16 v[24:27], v[168:171], v[222:225], v[24:27]
	v_mfma_f32_16x16x32_bf16 v[12:15], v[144:147], v[230:233], v[12:15]
	v_mfma_f32_16x16x32_bf16 v[8:11], v[168:171], v[230:233], v[8:11]
	v_mfma_f32_16x16x32_bf16 v[60:63], v[164:167], v[210:213], v[60:63]
	v_mfma_f32_16x16x32_bf16 v[56:59], v[186:189], v[210:213], v[56:59]
	v_mfma_f32_16x16x32_bf16 v[44:47], v[164:167], v[218:221], v[44:47]
	v_mfma_f32_16x16x32_bf16 v[40:43], v[186:189], v[218:221], v[40:43]
	v_mfma_f32_16x16x32_bf16 v[28:31], v[164:167], v[226:229], v[28:31]
	v_mfma_f32_16x16x32_bf16 v[24:27], v[186:189], v[226:229], v[24:27]
	v_mfma_f32_16x16x32_bf16 v[12:15], v[164:167], v[242:245], v[12:15]
	v_mfma_f32_16x16x32_bf16 v[8:11], v[186:189], v[242:245], v[8:11]
	s_setprio 0
	s_setprio 1
	v_mfma_f32_16x16x32_bf16 v[52:55], v[190:193], v[206:209], v[52:55]
	v_mfma_f32_16x16x32_bf16 v[48:51], v[198:201], v[206:209], v[48:51]
	v_mfma_f32_16x16x32_bf16 v[36:39], v[190:193], v[214:217], v[36:39]
	v_mfma_f32_16x16x32_bf16 v[32:35], v[198:201], v[214:217], v[32:35]
	v_mfma_f32_16x16x32_bf16 v[20:23], v[190:193], v[222:225], v[20:23]
	v_mfma_f32_16x16x32_bf16 v[16:19], v[198:201], v[222:225], v[16:19]
	v_mfma_f32_16x16x32_bf16 v[4:7], v[190:193], v[230:233], v[4:7]
	v_mfma_f32_16x16x32_bf16 v[0:3], v[198:201], v[230:233], v[0:3]
	v_mfma_f32_16x16x32_bf16 v[52:55], v[194:197], v[210:213], v[52:55]
	v_mfma_f32_16x16x32_bf16 v[48:51], v[202:205], v[210:213], v[48:51]
	v_mfma_f32_16x16x32_bf16 v[36:39], v[194:197], v[218:221], v[36:39]
	v_mfma_f32_16x16x32_bf16 v[32:35], v[202:205], v[218:221], v[32:35]
	v_mfma_f32_16x16x32_bf16 v[20:23], v[194:197], v[226:229], v[20:23]
	v_mfma_f32_16x16x32_bf16 v[16:19], v[202:205], v[226:229], v[16:19]
	v_mfma_f32_16x16x32_bf16 v[4:7], v[194:197], v[242:245], v[4:7]
	v_mfma_f32_16x16x32_bf16 v[0:3], v[202:205], v[242:245], v[0:3]
	s_setprio 0
	s_barrier
	s_setprio 2
	s_add_i32 s59, s59, 2
	s_add_u32 s14, s14, 0x100
	s_addc_u32 s15, s15, 0
	s_add_u32 s57, s57, 0x100
	s_addc_u32 s58, s58, 0
	s_cmp_gt_u32 s59, 13
	s_cbranch_scc0 .LBB0_449
	s_and_b64 vcc, exec, s[18:19]
	s_cbranch_vccz .LBB0_454
	s_barrier
	v_lshl_add_u32 v146, s54, 8, v150
	s_cmp_gt_i32 s53, 7
	s_mov_b64 s[14:15], -1
	s_cbranch_scc1 .LBB0_455

.LBB0_490:
	s_add_i32 s66, s6, 2
	s_add_u32 s67, s4, 0x80
	s_addc_u32 s7, s5, 0
	s_add_i32 s70, 0, 0x10000
	s_cmp_eq_u32 s60, s6
	s_cselect_b32 s7, s43, s7
	s_cselect_b32 s6, s42, s67
	v_add_u32_e32 v148, s70, v151
	s_cselect_b32 s69, s45, s15
	s_cselect_b32 s68, s44, s14
	s_add_i32 s67, 0, 0x14000
	ds_read_b128 v[140:143], v148
	ds_read_b128 v[144:147], v148 offset:1024
	ds_read_b128 v[162:165], v148 offset:2048
	ds_read_b128 v[166:169], v148 offset:3072
	v_add_u32_e32 v148, s67, v151
	ds_read_b128 v[170:173], v148
	ds_read_b128 v[186:189], v148 offset:1024
	ds_read_b128 v[190:193], v148 offset:2048
	ds_read_b128 v[194:197], v148 offset:3072
	v_lshl_add_u64 v[148:149], s[4:5], 0, v[136:137]
	s_add_i32 m0, s52, 0xc000
	ds_read_b128 v[198:201], v153
	ds_read_b128 v[202:205], v153 offset:1024
	ds_read_b128 v[206:209], v153 offset:2048
	ds_read_b128 v[210:213], v153 offset:3072
	ds_read_b128 v[214:217], v153 offset:4096
	ds_read_b128 v[218:221], v153 offset:5120
	ds_read_b128 v[222:225], v153 offset:6144
	ds_read_b128 v[226:229], v153 offset:7168
	global_load_lds_dwordx4 v[148:149], off
	v_lshl_add_u64 v[148:149], s[4:5], 0, v[138:139]
	s_add_i32 m0, s52, 0xe000
	s_nop 0
	global_load_lds_dwordx4 v[148:149], off
	s_setprio 0
	s_waitcnt vmcnt(8)
	s_waitcnt lgkmcnt(0)
	s_barrier
	s_setprio 1
	v_mfma_f32_16x16x32_bf16 v[126:129], v[140:143], v[198:201], v[126:129]
	v_mfma_f32_16x16x32_bf16 v[122:125], v[162:165], v[198:201], v[122:125]
	v_mfma_f32_16x16x32_bf16 v[110:113], v[140:143], v[206:209], v[110:113]
	v_mfma_f32_16x16x32_bf16 v[106:109], v[162:165], v[206:209], v[106:109]
	v_mfma_f32_16x16x32_bf16 v[92:95], v[140:143], v[214:217], v[92:95]
	v_mfma_f32_16x16x32_bf16 v[88:91], v[162:165], v[214:217], v[88:91]
	v_mfma_f32_16x16x32_bf16 v[76:79], v[140:143], v[222:225], v[76:79]
	v_mfma_f32_16x16x32_bf16 v[72:75], v[162:165], v[222:225], v[72:75]
	v_mfma_f32_16x16x32_bf16 v[126:129], v[144:147], v[202:205], v[126:129]
	v_mfma_f32_16x16x32_bf16 v[122:125], v[166:169], v[202:205], v[122:125]
	v_mfma_f32_16x16x32_bf16 v[110:113], v[144:147], v[210:213], v[110:113]
	v_mfma_f32_16x16x32_bf16 v[106:109], v[166:169], v[210:213], v[106:109]
	v_mfma_f32_16x16x32_bf16 v[92:95], v[144:147], v[218:221], v[92:95]
	v_mfma_f32_16x16x32_bf16 v[88:91], v[166:169], v[218:221], v[88:91]
	v_mfma_f32_16x16x32_bf16 v[76:79], v[144:147], v[226:229], v[76:79]
	v_mfma_f32_16x16x32_bf16 v[72:75], v[166:169], v[226:229], v[72:75]
	s_setprio 0
	s_setprio 1
	v_mfma_f32_16x16x32_bf16 v[118:121], v[170:173], v[198:201], v[118:121]
	v_mfma_f32_16x16x32_bf16 v[114:117], v[190:193], v[198:201], v[114:117]
	v_mfma_f32_16x16x32_bf16 v[102:105], v[170:173], v[206:209], v[102:105]
	v_mfma_f32_16x16x32_bf16 v[98:101], v[190:193], v[206:209], v[98:101]
	v_mfma_f32_16x16x32_bf16 v[84:87], v[170:173], v[214:217], v[84:87]
	v_mfma_f32_16x16x32_bf16 v[80:83], v[190:193], v[214:217], v[80:83]
	v_mfma_f32_16x16x32_bf16 v[68:71], v[170:173], v[222:225], v[68:71]
	v_mfma_f32_16x16x32_bf16 v[64:67], v[190:193], v[222:225], v[64:67]
	v_mfma_f32_16x16x32_bf16 v[118:121], v[186:189], v[202:205], v[118:121]
	v_mfma_f32_16x16x32_bf16 v[114:117], v[194:197], v[202:205], v[114:117]
	v_mfma_f32_16x16x32_bf16 v[102:105], v[186:189], v[210:213], v[102:105]
	v_mfma_f32_16x16x32_bf16 v[98:101], v[194:197], v[210:213], v[98:101]
	v_mfma_f32_16x16x32_bf16 v[84:87], v[186:189], v[218:221], v[84:87]
	v_mfma_f32_16x16x32_bf16 v[80:83], v[194:197], v[218:221], v[80:83]
	v_mfma_f32_16x16x32_bf16 v[68:71], v[186:189], v[226:229], v[68:71]
	v_mfma_f32_16x16x32_bf16 v[64:67], v[194:197], v[226:229], v[64:67]
	s_setprio 0
	s_barrier
	s_setprio 2
	s_add_i32 s70, s70, s51
	v_lshl_add_u64 v[148:149], s[68:69], 0, v[96:97]
	s_mov_b32 m0, s70
	ds_read_b128 v[198:201], v153 offset:16384
	ds_read_b128 v[202:205], v153 offset:17408
	ds_read_b128 v[206:209], v153 offset:18432
	ds_read_b128 v[210:213], v153 offset:19456
	ds_read_b128 v[214:217], v153 offset:20480
	ds_read_b128 v[218:221], v153 offset:21504
	ds_read_b128 v[222:225], v153 offset:22528
	ds_read_b128 v[226:229], v153 offset:23552
	global_load_lds_dwordx4 v[148:149], off
	s_add_i32 m0, s70, 0x2000
	v_lshl_add_u64 v[154:155], s[68:69], 0, v[130:131]
	s_add_u32 s68, s68, s46
	s_addc_u32 s69, s69, 0
	s_add_i32 s67, s67, s51
	global_load_lds_dwordx4 v[154:155], off
	v_lshl_add_u64 v[156:157], s[68:69], 0, v[96:97]
	s_mov_b32 m0, s67
	v_lshl_add_u64 v[158:159], s[68:69], 0, v[130:131]
	global_load_lds_dwordx4 v[156:157], off
	s_add_i32 m0, s67, 0x2000
	v_lshl_add_u64 v[182:183], s[6:7], 0, v[134:135]
	global_load_lds_dwordx4 v[158:159], off
	s_mov_b32 m0, s52
	v_lshl_add_u64 v[184:185], s[6:7], 0, v[132:133]
	global_load_lds_dwordx4 v[182:183], off
	s_mov_b32 m0, s53
	s_nop 0
	global_load_lds_dwordx4 v[184:185], off
	s_setprio 0
	s_waitcnt vmcnt(8)
	s_waitcnt lgkmcnt(0)
	s_barrier
	s_setprio 1
	v_mfma_f32_16x16x32_bf16 v[60:63], v[140:143], v[198:201], v[60:63]
	v_mfma_f32_16x16x32_bf16 v[56:59], v[162:165], v[198:201], v[56:59]
	v_mfma_f32_16x16x32_bf16 v[44:47], v[140:143], v[206:209], v[44:47]
	v_mfma_f32_16x16x32_bf16 v[40:43], v[162:165], v[206:209], v[40:43]
	v_mfma_f32_16x16x32_bf16 v[28:31], v[140:143], v[214:217], v[28:31]
	v_mfma_f32_16x16x32_bf16 v[24:27], v[162:165], v[214:217], v[24:27]
	v_mfma_f32_16x16x32_bf16 v[12:15], v[140:143], v[222:225], v[12:15]
	v_mfma_f32_16x16x32_bf16 v[8:11], v[162:165], v[222:225], v[8:11]
	v_mfma_f32_16x16x32_bf16 v[60:63], v[144:147], v[202:205], v[60:63]
	v_mfma_f32_16x16x32_bf16 v[56:59], v[166:169], v[202:205], v[56:59]
	v_mfma_f32_16x16x32_bf16 v[44:47], v[144:147], v[210:213], v[44:47]
	v_mfma_f32_16x16x32_bf16 v[40:43], v[166:169], v[210:213], v[40:43]
	v_mfma_f32_16x16x32_bf16 v[28:31], v[144:147], v[218:221], v[28:31]
	v_mfma_f32_16x16x32_bf16 v[24:27], v[166:169], v[218:221], v[24:27]
	v_mfma_f32_16x16x32_bf16 v[12:15], v[144:147], v[226:229], v[12:15]
	v_mfma_f32_16x16x32_bf16 v[8:11], v[166:169], v[226:229], v[8:11]
	s_setprio 0
	s_setprio 1
	v_mfma_f32_16x16x32_bf16 v[52:55], v[170:173], v[198:201], v[52:55]
	v_mfma_f32_16x16x32_bf16 v[48:51], v[190:193], v[198:201], v[48:51]
	v_mfma_f32_16x16x32_bf16 v[36:39], v[170:173], v[206:209], v[36:39]
	v_mfma_f32_16x16x32_bf16 v[32:35], v[190:193], v[206:209], v[32:35]
	v_mfma_f32_16x16x32_bf16 v[20:23], v[170:173], v[214:217], v[20:23]
	v_mfma_f32_16x16x32_bf16 v[16:19], v[190:193], v[214:217], v[16:19]
	v_mfma_f32_16x16x32_bf16 v[4:7], v[170:173], v[222:225], v[4:7]
	v_mfma_f32_16x16x32_bf16 v[0:3], v[190:193], v[222:225], v[0:3]
	v_mfma_f32_16x16x32_bf16 v[52:55], v[186:189], v[202:205], v[52:55]
	v_mfma_f32_16x16x32_bf16 v[48:51], v[194:197], v[202:205], v[48:51]
	v_mfma_f32_16x16x32_bf16 v[36:39], v[186:189], v[210:213], v[36:39]
	v_mfma_f32_16x16x32_bf16 v[32:35], v[194:197], v[210:213], v[32:35]
	v_mfma_f32_16x16x32_bf16 v[20:23], v[186:189], v[218:221], v[20:23]
	v_mfma_f32_16x16x32_bf16 v[16:19], v[194:197], v[218:221], v[16:19]
	v_mfma_f32_16x16x32_bf16 v[4:7], v[186:189], v[226:229], v[4:7]
	v_mfma_f32_16x16x32_bf16 v[0:3], v[194:197], v[226:229], v[0:3]
	s_setprio 0
	s_barrier
	s_setprio 2
	s_add_i32 s67, 0, 0x18000
	s_add_i32 s68, 0, 0x1c000
	v_add_u32_e32 v166, s67, v151
	v_add_u32_e32 v194, s68, v151
	ds_read_b128 v[140:143], v166
	ds_read_b128 v[144:147], v166 offset:1024
	ds_read_b128 v[162:165], v166 offset:2048
	ds_read_b128 v[166:169], v166 offset:3072
	ds_read_b128 v[170:173], v194
	ds_read_b128 v[186:189], v194 offset:1024
	ds_read_b128 v[190:193], v194 offset:2048
	ds_read_b128 v[194:197], v194 offset:3072
	s_add_u32 s6, s6, s46
	s_addc_u32 s7, s7, 0
	s_mov_b32 m0, s54
	v_lshl_add_u64 v[230:231], s[6:7], 0, v[134:135]
	ds_read_b128 v[198:201], v153 offset:32768
	ds_read_b128 v[202:205], v153 offset:33792
	ds_read_b128 v[206:209], v153 offset:34816
	ds_read_b128 v[210:213], v153 offset:35840
	ds_read_b128 v[214:217], v153 offset:36864
	ds_read_b128 v[218:221], v153 offset:37888
	ds_read_b128 v[222:225], v153 offset:38912
	ds_read_b128 v[226:229], v153 offset:39936
	global_load_lds_dwordx4 v[230:231], off
	v_lshl_add_u64 v[230:231], s[6:7], 0, v[132:133]
	s_mov_b32 m0, s55
	s_nop 0
	global_load_lds_dwordx4 v[230:231], off
	s_setprio 0
	s_waitcnt vmcnt(8)
	s_waitcnt lgkmcnt(0)
	s_barrier
	s_setprio 1
	v_mfma_f32_16x16x32_bf16 v[126:129], v[140:143], v[198:201], v[126:129]
	v_mfma_f32_16x16x32_bf16 v[122:125], v[162:165], v[198:201], v[122:125]
	v_mfma_f32_16x16x32_bf16 v[110:113], v[140:143], v[206:209], v[110:113]
	v_mfma_f32_16x16x32_bf16 v[106:109], v[162:165], v[206:209], v[106:109]
	v_mfma_f32_16x16x32_bf16 v[92:95], v[140:143], v[214:217], v[92:95]
	v_mfma_f32_16x16x32_bf16 v[88:91], v[162:165], v[214:217], v[88:91]
	v_mfma_f32_16x16x32_bf16 v[76:79], v[140:143], v[222:225], v[76:79]
	v_mfma_f32_16x16x32_bf16 v[72:75], v[162:165], v[222:225], v[72:75]
	v_mfma_f32_16x16x32_bf16 v[126:129], v[144:147], v[202:205], v[126:129]
	v_mfma_f32_16x16x32_bf16 v[122:125], v[166:169], v[202:205], v[122:125]
	v_mfma_f32_16x16x32_bf16 v[110:113], v[144:147], v[210:213], v[110:113]
	v_mfma_f32_16x16x32_bf16 v[106:109], v[166:169], v[210:213], v[106:109]
	v_mfma_f32_16x16x32_bf16 v[92:95], v[144:147], v[218:221], v[92:95]
	v_mfma_f32_16x16x32_bf16 v[88:91], v[166:169], v[218:221], v[88:91]
	v_mfma_f32_16x16x32_bf16 v[76:79], v[144:147], v[226:229], v[76:79]
	v_mfma_f32_16x16x32_bf16 v[72:75], v[166:169], v[226:229], v[72:75]
	s_setprio 0
	s_setprio 1
	v_mfma_f32_16x16x32_bf16 v[118:121], v[170:173], v[198:201], v[118:121]
	v_mfma_f32_16x16x32_bf16 v[114:117], v[190:193], v[198:201], v[114:117]
	v_mfma_f32_16x16x32_bf16 v[102:105], v[170:173], v[206:209], v[102:105]
	v_mfma_f32_16x16x32_bf16 v[98:101], v[190:193], v[206:209], v[98:101]
	v_mfma_f32_16x16x32_bf16 v[84:87], v[170:173], v[214:217], v[84:87]
	v_mfma_f32_16x16x32_bf16 v[80:83], v[190:193], v[214:217], v[80:83]
	v_mfma_f32_16x16x32_bf16 v[68:71], v[170:173], v[222:225], v[68:71]
	v_mfma_f32_16x16x32_bf16 v[64:67], v[190:193], v[222:225], v[64:67]
	v_mfma_f32_16x16x32_bf16 v[118:121], v[186:189], v[202:205], v[118:121]
	v_mfma_f32_16x16x32_bf16 v[114:117], v[194:197], v[202:205], v[114:117]
	v_mfma_f32_16x16x32_bf16 v[102:105], v[186:189], v[210:213], v[102:105]
	v_mfma_f32_16x16x32_bf16 v[98:101], v[194:197], v[210:213], v[98:101]
	v_mfma_f32_16x16x32_bf16 v[84:87], v[186:189], v[218:221], v[84:87]
	v_mfma_f32_16x16x32_bf16 v[80:83], v[194:197], v[218:221], v[80:83]
	v_mfma_f32_16x16x32_bf16 v[68:71], v[186:189], v[226:229], v[68:71]
	v_mfma_f32_16x16x32_bf16 v[64:67], v[194:197], v[226:229], v[64:67]
	s_setprio 0
	s_barrier
	s_setprio 2
	s_add_i32 s6, s67, s51
	v_lshl_add_u64 v[148:149], v[148:149], 0, s[16:17]
	s_mov_b32 m0, s6
	ds_read_b128 v[198:201], v153 offset:49152
	ds_read_b128 v[202:205], v153 offset:50176
	ds_read_b128 v[206:209], v153 offset:51200
	ds_read_b128 v[210:213], v153 offset:52224
	ds_read_b128 v[214:217], v153 offset:53248
	ds_read_b128 v[218:221], v153 offset:54272
	ds_read_b128 v[222:225], v153 offset:55296
	ds_read_b128 v[226:229], v153 offset:56320
	global_load_lds_dwordx4 v[148:149], off
	v_lshl_add_u64 v[148:149], v[154:155], 0, s[16:17]
	s_add_i32 m0, s6, 0x2000
	s_add_i32 s6, s68, s51
	global_load_lds_dwordx4 v[148:149], off
	v_lshl_add_u64 v[148:149], v[156:157], 0, s[16:17]
	s_mov_b32 m0, s6
	s_nop 0
	global_load_lds_dwordx4 v[148:149], off
	v_lshl_add_u64 v[148:149], v[158:159], 0, s[16:17]
	s_add_i32 m0, s6, 0x2000
	s_nop 0
	global_load_lds_dwordx4 v[148:149], off
	v_lshl_add_u64 v[148:149], v[182:183], 0, s[16:17]
	s_mov_b32 m0, s56
	s_nop 0
	global_load_lds_dwordx4 v[148:149], off
	v_lshl_add_u64 v[148:149], v[184:185], 0, s[16:17]
	s_mov_b32 m0, s57
	s_nop 0
	global_load_lds_dwordx4 v[148:149], off
	s_setprio 0
	s_waitcnt vmcnt(8)
	s_waitcnt lgkmcnt(0)
	s_barrier
	s_setprio 1
	v_mfma_f32_16x16x32_bf16 v[60:63], v[140:143], v[198:201], v[60:63]
	v_mfma_f32_16x16x32_bf16 v[56:59], v[162:165], v[198:201], v[56:59]
	v_mfma_f32_16x16x32_bf16 v[44:47], v[140:143], v[206:209], v[44:47]
	v_mfma_f32_16x16x32_bf16 v[40:43], v[162:165], v[206:209], v[40:43]
	v_mfma_f32_16x16x32_bf16 v[28:31], v[140:143], v[214:217], v[28:31]
	v_mfma_f32_16x16x32_bf16 v[24:27], v[162:165], v[214:217], v[24:27]
	v_mfma_f32_16x16x32_bf16 v[12:15], v[140:143], v[222:225], v[12:15]
	v_mfma_f32_16x16x32_bf16 v[8:11], v[162:165], v[222:225], v[8:11]
	v_mfma_f32_16x16x32_bf16 v[60:63], v[144:147], v[202:205], v[60:63]
	v_mfma_f32_16x16x32_bf16 v[56:59], v[166:169], v[202:205], v[56:59]
	v_mfma_f32_16x16x32_bf16 v[44:47], v[144:147], v[210:213], v[44:47]
	v_mfma_f32_16x16x32_bf16 v[40:43], v[166:169], v[210:213], v[40:43]
	v_mfma_f32_16x16x32_bf16 v[28:31], v[144:147], v[218:221], v[28:31]
	v_mfma_f32_16x16x32_bf16 v[24:27], v[166:169], v[218:221], v[24:27]
	v_mfma_f32_16x16x32_bf16 v[12:15], v[144:147], v[226:229], v[12:15]
	v_mfma_f32_16x16x32_bf16 v[8:11], v[166:169], v[226:229], v[8:11]
	s_setprio 0
	s_setprio 1
	v_mfma_f32_16x16x32_bf16 v[52:55], v[170:173], v[198:201], v[52:55]
	v_mfma_f32_16x16x32_bf16 v[48:51], v[190:193], v[198:201], v[48:51]
	v_mfma_f32_16x16x32_bf16 v[36:39], v[170:173], v[206:209], v[36:39]
	v_mfma_f32_16x16x32_bf16 v[32:35], v[190:193], v[206:209], v[32:35]
	v_mfma_f32_16x16x32_bf16 v[20:23], v[170:173], v[214:217], v[20:23]
	v_mfma_f32_16x16x32_bf16 v[16:19], v[190:193], v[214:217], v[16:19]
	v_mfma_f32_16x16x32_bf16 v[4:7], v[170:173], v[222:225], v[4:7]
	v_mfma_f32_16x16x32_bf16 v[0:3], v[190:193], v[222:225], v[0:3]
	v_mfma_f32_16x16x32_bf16 v[52:55], v[186:189], v[202:205], v[52:55]
	v_mfma_f32_16x16x32_bf16 v[48:51], v[194:197], v[202:205], v[48:51]
	v_mfma_f32_16x16x32_bf16 v[36:39], v[186:189], v[210:213], v[36:39]
	v_mfma_f32_16x16x32_bf16 v[32:35], v[194:197], v[210:213], v[32:35]
	v_mfma_f32_16x16x32_bf16 v[20:23], v[186:189], v[218:221], v[20:23]
	v_mfma_f32_16x16x32_bf16 v[16:19], v[194:197], v[218:221], v[16:19]
	v_mfma_f32_16x16x32_bf16 v[4:7], v[186:189], v[226:229], v[4:7]
	v_mfma_f32_16x16x32_bf16 v[0:3], v[194:197], v[226:229], v[0:3]
	s_setprio 0
	s_barrier
	s_setprio 2
	s_add_u32 s4, s4, 0x100
	s_addc_u32 s5, s5, 0
	s_add_u32 s14, s14, 0x100
	s_addc_u32 s15, s15, 0
	s_cmp_ge_u32 s66, s59
	s_mov_b32 s6, s66
	s_cbranch_scc0 .LBB0_490
	s_and_b64 vcc, exec, s[36:37]
	s_cbranch_vccz .LBB0_493
	s_barrier
